# hand-written conformer conv s-loop: weights staged to LDS once per tile, 8-deep input-row register ring with counted vmcnt, only live taps, accumulators handed to the existing epilogue
# speedup vs baseline: 1.0067x; 1.0067x over previous
; DEV int ltid() { int t = threadIdx.x; asm volatile("" : "+v"(t)); return t; }
; DEV float lo_bf(unsigned u) { return __uint_as_float(u << 16); }
; DEV float hi_bf(unsigned u) { return __uint_as_float(u & 0xffff0000u); }
; DEV void conv_tile(const Params& p, int l, int tile, char* smem) {
;     ...
;   const int r0 = tile * 64;
;   int s_lo, s_hi;
;   if (r0 < T_LAT) { s_lo = r0 & ~4095; s_hi = s_lo + SEQ; } else { s_lo = T_LAT + ((r0 - T_LAT) & ~255); s_hi = s_lo + CTXL; }
;   const int tid = ltid(), lane = tid & 63, w = tid >> 6, c0 = lane * 8;
;   const int t0 = r0 + w * 8;
;   const float* wp = p.conv_dw_w + (size_t)l * 31 * 512 + c0;
;   float acc[8][8];
;   {
;     const f32x4 b0 = *(const f32x4*)(p.conv_dw_b + l * 512 + c0), b1 = *(const f32x4*)(p.conv_dw_b + l * 512 + c0 + 4);
; #pragma unroll
;     for (int t = 0; t < 8; ++t)
; #pragma unroll
;       for (int j = 0; j < 4; ++j) { acc[t][j] = b0[j]; acc[t][4 + j] = b1[j]; }
;   }
;   f32x4 wk[8][2];
; #pragma unroll
;   for (int q = 0; q < 8; ++q) { wk[q][0] = (f32x4){0.f, 0.f, 0.f, 0.f}; wk[q][1] = (f32x4){0.f, 0.f, 0.f, 0.f}; }
; #pragma unroll 4
;   for (int s = 0; s < 40; ++s) {
;     const int rr = t0 - 15 + s;
;     u32x4 uv = {0u, 0u, 0u, 0u};
;     if (rr >= s_lo && rr < s_hi) uv = *(const u32x4*)(ZU + (size_t)rr * 512 + c0);
;     float u[8];
; #pragma unroll
;     for (int q = 0; q < 4; ++q) { u[2 * q] = lo_bf(uv[q]); u[2 * q + 1] = hi_bf(uv[q]); }
; #pragma unroll
;     for (int q = 7; q > 0; --q) { wk[q][0] = wk[q - 1][0]; wk[q][1] = wk[q - 1][1]; }
;     wk[0][0] = (f32x4){0.f, 0.f, 0.f, 0.f}; wk[0][1] = (f32x4){0.f, 0.f, 0.f, 0.f};
;     if (s <= 30) { wk[0][0] = *(const f32x4*)(wp + s * 512); wk[0][1] = *(const f32x4*)(wp + s * 512 + 4); }
; DEV void branch_phase(const Params& p, int l, char* smem) {
;     ...
;     else if (L < 1632) { if (!(last && L - 1088 >= 512)) conv_tile(p, l, L - 1088, smem); }
.LBB0_570:
	s_andn2_b64 vcc, exec, s[0:1]
	s_cbranch_vccnz .LBB0_591
	s_cmpk_gt_u32 s40, 0x63f
	v_readlane_b32 s30, v255, 46
	s_cselect_b64 s[0:1], -1, 0
	v_readlane_b32 s31, v255, 47
	s_and_b64 s[0:1], s[30:31], s[0:1]
	s_and_b64 vcc, exec, s[0:1]
	s_cbranch_vccnz .LBB0_591
	s_add_i32 s0, s40, 0xfffffbc0
	s_lshl_b32 s30, s0, 6
	s_and_b32 s36, s30, 0xfffff000
	s_add_i32 s31, s36, 0x1000
	s_and_b32 s38, s30, 0xffffff00
	s_add_i32 s39, s38, 0x100
	s_cmp_lt_u32 s30, 0x8000
	s_cselect_b32 s36, s36, s38
	s_cselect_b32 s31, s31, s39
	s_add_i32 s39, s31, -1
	v_and_b32_e32 v102, 63, v226
	v_lshlrev_b32_e32 v98, 3, v102
	v_lshrrev_b32_e32 v99, 6, v226
	v_lshlrev_b32_e32 v99, 3, v99
	v_lshlrev_b32_e32 v100, 4, v102
	v_lshlrev_b32_e32 v101, 5, v102
	v_readfirstlane_b32 s37, v226
	v_lshlrev_b32_e32 v103, 4, v226
	s_lshr_b32 s37, s37, 6
	s_lshl_b32 s101, s37, 3
	s_add_i32 s37, s30, s101
	s_add_i32 s37, s37, -15
	s_add_u32 s0, s50, 0xffffe7f0
	s_addc_u32 s1, s51, -1
	global_load_dwordx4 v[16:19], v103, s[0:1]
	s_add_u32 s0, s0, 0x2000
	s_addc_u32 s1, s1, 0
	global_load_dwordx4 v[20:23], v103, s[0:1]
	s_add_u32 s0, s0, 0x2000
	s_addc_u32 s1, s1, 0
	global_load_dwordx4 v[24:27], v103, s[0:1]
	s_add_u32 s0, s0, 0x2000
	s_addc_u32 s1, s1, 0
	global_load_dwordx4 v[28:31], v103, s[0:1]
	s_add_u32 s0, s0, 0x2000
	s_addc_u32 s1, s1, 0
	global_load_dwordx4 v[32:35], v103, s[0:1]
	s_add_u32 s0, s0, 0x2000
	s_addc_u32 s1, s1, 0
	global_load_dwordx4 v[36:39], v103, s[0:1]
	s_add_u32 s0, s0, 0x2000
	s_addc_u32 s1, s1, 0
	global_load_dwordx4 v[40:43], v103, s[0:1]
	s_add_u32 s0, s0, 0x2000
	s_addc_u32 s1, s1, 0
	s_cmp_gt_u32 s101, 40
	s_cbranch_scc1 .Lcv_st7
	global_load_dwordx4 v[44:47], v103, s[0:1]
.Lcv_st7:
	v_lshlrev_b32_e32 v102, 2, v98
	global_load_dwordx4 v[4:7], v102, s[42:43]
	global_load_dwordx4 v[12:15], v102, s[42:43] offset:16
	s_add_i32 s38, s37, 0
	s_max_i32 s38, s38, s36
	s_min_i32 s38, s38, s39
	s_lshl_b32 s38, s38, 10
	s_add_u32 s0, s74, s38
	s_addc_u32 s1, s75, 0
	global_load_dwordx4 v[144:147], v100, s[0:1]
	s_add_i32 s38, s37, 1
	s_max_i32 s38, s38, s36
	s_min_i32 s38, s38, s39
	s_lshl_b32 s38, s38, 10
	s_add_u32 s0, s74, s38
	s_addc_u32 s1, s75, 0
	global_load_dwordx4 v[148:151], v100, s[0:1]
	s_add_i32 s38, s37, 2
	s_max_i32 s38, s38, s36
	s_min_i32 s38, s38, s39
	s_lshl_b32 s38, s38, 10
	s_add_u32 s0, s74, s38
	s_addc_u32 s1, s75, 0
	global_load_dwordx4 v[152:155], v100, s[0:1]
	s_add_i32 s38, s37, 3
	s_max_i32 s38, s38, s36
	s_min_i32 s38, s38, s39
	s_lshl_b32 s38, s38, 10
	s_add_u32 s0, s74, s38
	s_addc_u32 s1, s75, 0
	global_load_dwordx4 v[156:159], v100, s[0:1]
	s_add_i32 s38, s37, 4
	s_max_i32 s38, s38, s36
	s_min_i32 s38, s38, s39
	s_lshl_b32 s38, s38, 10
	s_add_u32 s0, s74, s38
	s_addc_u32 s1, s75, 0
	global_load_dwordx4 v[160:163], v100, s[0:1]
	s_add_i32 s38, s37, 5
	s_max_i32 s38, s38, s36
	s_min_i32 s38, s38, s39
	s_lshl_b32 s38, s38, 10
	s_add_u32 s0, s74, s38
	s_addc_u32 s1, s75, 0
	global_load_dwordx4 v[164:167], v100, s[0:1]
	s_add_i32 s38, s37, 6
	s_max_i32 s38, s38, s36
	s_min_i32 s38, s38, s39
	s_lshl_b32 s38, s38, 10
	s_add_u32 s0, s74, s38
	s_addc_u32 s1, s75, 0
	global_load_dwordx4 v[168:171], v100, s[0:1]
	s_add_i32 s38, s37, 7
	s_max_i32 s38, s38, s36
	s_min_i32 s38, s38, s39
	s_lshl_b32 s38, s38, 10
	s_add_u32 s0, s74, s38
	s_addc_u32 s1, s75, 0
	global_load_dwordx4 v[172:175], v100, s[0:1]
	s_cmp_gt_u32 s101, 40
	s_cbranch_scc1 .Lcv_w7
	s_waitcnt vmcnt(10)
	ds_write_b128 v103, v[16:19] offset:0
	ds_write_b128 v103, v[20:23] offset:8192
	ds_write_b128 v103, v[24:27] offset:16384
	ds_write_b128 v103, v[28:31] offset:24576
	ds_write_b128 v103, v[32:35] offset:32768
	ds_write_b128 v103, v[36:39] offset:40960
	ds_write_b128 v103, v[40:43] offset:49152
	ds_write_b128 v103, v[44:47] offset:57344
	s_branch .Lcv_wd
.Lcv_w7:
	s_waitcnt vmcnt(10)
	ds_write_b128 v103, v[16:19] offset:0
	ds_write_b128 v103, v[20:23] offset:8192
	ds_write_b128 v103, v[24:27] offset:16384
	ds_write_b128 v103, v[28:31] offset:24576
	ds_write_b128 v103, v[32:35] offset:32768
	ds_write_b128 v103, v[36:39] offset:40960
	ds_write_b128 v103, v[40:43] offset:49152
.Lcv_wd:
	s_waitcnt vmcnt(8) lgkmcnt(0)
	s_barrier
	v_mov_b32_e32 v142, v4
	v_mov_b32_e32 v143, v5
	v_mov_b32_e32 v138, v6
	v_mov_b32_e32 v139, v7
	v_mov_b32_e32 v140, v12
	v_mov_b32_e32 v141, v13
	v_mov_b32_e32 v136, v14
	v_mov_b32_e32 v137, v15
	v_mov_b32_e32 v110, v4
	v_mov_b32_e32 v111, v5
	v_mov_b32_e32 v106, v6
	v_mov_b32_e32 v107, v7
	v_mov_b32_e32 v108, v12
	v_mov_b32_e32 v109, v13
	v_mov_b32_e32 v104, v14
	v_mov_b32_e32 v105, v15
	v_mov_b32_e32 v94, v4
	v_mov_b32_e32 v95, v5
	v_mov_b32_e32 v90, v6
	v_mov_b32_e32 v91, v7
	v_mov_b32_e32 v92, v12
	v_mov_b32_e32 v93, v13
	v_mov_b32_e32 v88, v14
	v_mov_b32_e32 v89, v15
	v_mov_b32_e32 v86, v4
	v_mov_b32_e32 v87, v5
	v_mov_b32_e32 v82, v6
	v_mov_b32_e32 v83, v7
	v_mov_b32_e32 v84, v12
	v_mov_b32_e32 v85, v13
	v_mov_b32_e32 v80, v14
	v_mov_b32_e32 v81, v15
	v_mov_b32_e32 v78, v4
	v_mov_b32_e32 v79, v5
	v_mov_b32_e32 v74, v6
	v_mov_b32_e32 v75, v7
	v_mov_b32_e32 v76, v12
	v_mov_b32_e32 v77, v13
	v_mov_b32_e32 v72, v14
	v_mov_b32_e32 v73, v15
	v_mov_b32_e32 v70, v4
	v_mov_b32_e32 v71, v5
	v_mov_b32_e32 v66, v6
	v_mov_b32_e32 v67, v7
	v_mov_b32_e32 v68, v12
	v_mov_b32_e32 v69, v13
	v_mov_b32_e32 v64, v14
	v_mov_b32_e32 v65, v15
	v_mov_b32_e32 v62, v4
	v_mov_b32_e32 v63, v5
	v_mov_b32_e32 v58, v6
	v_mov_b32_e32 v59, v7
	v_mov_b32_e32 v60, v12
	v_mov_b32_e32 v61, v13
	v_mov_b32_e32 v56, v14
	v_mov_b32_e32 v57, v15
	ds_read_b128 v[16:19], v101
	ds_read_b128 v[20:23], v101 offset:16
	s_waitcnt vmcnt(7)
	v_lshlrev_b32_e32 v176, 16, v144
	v_and_b32_e32 v177, 0xffff0000, v144
	v_lshlrev_b32_e32 v178, 16, v145
	v_and_b32_e32 v179, 0xffff0000, v145
	v_lshlrev_b32_e32 v180, 16, v146
	v_and_b32_e32 v181, 0xffff0000, v146
	v_lshlrev_b32_e32 v182, 16, v147
	v_and_b32_e32 v183, 0xffff0000, v147
	s_add_i32 s100, s37, 0
	s_cmp_ge_i32 s100, s36
	s_cselect_b32 s101, 1, 0
	s_cmp_lt_i32 s100, s31
	s_cselect_b32 s38, 1, 0
	s_and_b32 s101, s101, s38
	s_cbranch_scc1 .Lcv_ok0
	v_mov_b32_e32 v176, 0
	v_mov_b32_e32 v177, 0
	v_mov_b32_e32 v178, 0
	v_mov_b32_e32 v179, 0
	v_mov_b32_e32 v180, 0
	v_mov_b32_e32 v181, 0
	v_mov_b32_e32 v182, 0
	v_mov_b32_e32 v183, 0
; DEV float lo_bf(unsigned u) { return __uint_as_float(u << 16); }
; DEV float hi_bf(unsigned u) { return __uint_as_float(u & 0xffff0000u); }
; DEV void conv_tile(const Params& p, int l, int tile, char* smem) {
;     ...
;   for (int s = 0; s < 40; ++s) {
;     const int rr = t0 - 15 + s;
;     u32x4 uv = {0u, 0u, 0u, 0u};
;     if (rr >= s_lo && rr < s_hi) uv = *(const u32x4*)(ZU + (size_t)rr * 512 + c0);
;     float u[8];
; #pragma unroll
;     for (int q = 0; q < 4; ++q) { u[2 * q] = lo_bf(uv[q]); u[2 * q + 1] = hi_bf(uv[q]); }
; #pragma unroll
;     for (int q = 7; q > 0; --q) { wk[q][0] = wk[q - 1][0]; wk[q][1] = wk[q - 1][1]; }
;     wk[0][0] = (f32x4){0.f, 0.f, 0.f, 0.f}; wk[0][1] = (f32x4){0.f, 0.f, 0.f, 0.f};
;     if (s <= 30) { wk[0][0] = *(const f32x4*)(wp + s * 512); wk[0][1] = *(const f32x4*)(wp + s * 512 + 4); }
; #pragma unroll
;     for (int t = 0; t < 8; ++t) {
; #pragma unroll
;       for (int j = 0; j < 4; ++j) { acc[t][j] += wk[t][0][j] * u[j]; acc[t][4 + j] += wk[t][1][j] * u[4 + j]; }
;     }
;   }
.Lcv_ok0:
	s_add_i32 s38, s37, 8
	s_max_i32 s38, s38, s36
	s_min_i32 s38, s38, s39
	s_lshl_b32 s38, s38, 10
	s_add_u32 s0, s74, s38
	s_addc_u32 s1, s75, 0
	global_load_dwordx4 v[144:147], v100, s[0:1]
	ds_read_b128 v[24:27], v101 offset:2048
	ds_read_b128 v[28:31], v101 offset:2064
	s_waitcnt lgkmcnt(2)
	v_pk_fma_f32 v[4:5], v[16:17], v[176:177], v[4:5]
	v_pk_fma_f32 v[6:7], v[18:19], v[178:179], v[6:7]
	v_pk_fma_f32 v[12:13], v[20:21], v[180:181], v[12:13]
	v_pk_fma_f32 v[14:15], v[22:23], v[182:183], v[14:15]
	s_waitcnt vmcnt(7)
	v_lshlrev_b32_e32 v186, 16, v148
	v_and_b32_e32 v187, 0xffff0000, v148
	v_lshlrev_b32_e32 v190, 16, v149
	v_and_b32_e32 v191, 0xffff0000, v149
	v_lshlrev_b32_e32 v192, 16, v150
	v_and_b32_e32 v193, 0xffff0000, v150
	v_lshlrev_b32_e32 v194, 16, v151
	v_and_b32_e32 v195, 0xffff0000, v151
	s_add_i32 s100, s37, 1
	s_cmp_ge_i32 s100, s36
	s_cselect_b32 s101, 1, 0
	s_cmp_lt_i32 s100, s31
	s_cselect_b32 s38, 1, 0
	s_and_b32 s101, s101, s38
	s_cbranch_scc1 .Lcv_ok1
	v_mov_b32_e32 v186, 0
	v_mov_b32_e32 v187, 0
	v_mov_b32_e32 v190, 0
	v_mov_b32_e32 v191, 0
	v_mov_b32_e32 v192, 0
	v_mov_b32_e32 v193, 0
	v_mov_b32_e32 v194, 0
	v_mov_b32_e32 v195, 0
.Lcv_ok1:
	s_add_i32 s38, s37, 9
	s_max_i32 s38, s38, s36
	s_min_i32 s38, s38, s39
	s_lshl_b32 s38, s38, 10
	s_add_u32 s0, s74, s38
	s_addc_u32 s1, s75, 0
	global_load_dwordx4 v[148:151], v100, s[0:1]
	ds_read_b128 v[32:35], v101 offset:4096
	ds_read_b128 v[36:39], v101 offset:4112
	s_waitcnt lgkmcnt(2)
	v_pk_fma_f32 v[4:5], v[24:25], v[186:187], v[4:5]
	v_pk_fma_f32 v[6:7], v[26:27], v[190:191], v[6:7]
	v_pk_fma_f32 v[12:13], v[28:29], v[192:193], v[12:13]
	v_pk_fma_f32 v[14:15], v[30:31], v[194:195], v[14:15]
	v_pk_fma_f32 v[142:143], v[16:17], v[186:187], v[142:143]
	v_pk_fma_f32 v[138:139], v[18:19], v[190:191], v[138:139]
	v_pk_fma_f32 v[140:141], v[20:21], v[192:193], v[140:141]
	v_pk_fma_f32 v[136:137], v[22:23], v[194:195], v[136:137]
	s_waitcnt vmcnt(7)
	v_lshlrev_b32_e32 v176, 16, v152
	v_and_b32_e32 v177, 0xffff0000, v152
	v_lshlrev_b32_e32 v178, 16, v153
	v_and_b32_e32 v179, 0xffff0000, v153
	v_lshlrev_b32_e32 v180, 16, v154
	v_and_b32_e32 v181, 0xffff0000, v154
	v_lshlrev_b32_e32 v182, 16, v155
	v_and_b32_e32 v183, 0xffff0000, v155
	s_add_i32 s100, s37, 2
	s_cmp_ge_i32 s100, s36
	s_cselect_b32 s101, 1, 0
	s_cmp_lt_i32 s100, s31
	s_cselect_b32 s38, 1, 0
	s_and_b32 s101, s101, s38
	s_cbranch_scc1 .Lcv_ok2
	v_mov_b32_e32 v176, 0
	v_mov_b32_e32 v177, 0
	v_mov_b32_e32 v178, 0
	v_mov_b32_e32 v179, 0
	v_mov_b32_e32 v180, 0
	v_mov_b32_e32 v181, 0
	v_mov_b32_e32 v182, 0
	v_mov_b32_e32 v183, 0
.Lcv_ok2:
	s_add_i32 s38, s37, 10
	s_max_i32 s38, s38, s36
	s_min_i32 s38, s38, s39
	s_lshl_b32 s38, s38, 10
	s_add_u32 s0, s74, s38
	s_addc_u32 s1, s75, 0
	global_load_dwordx4 v[152:155], v100, s[0:1]
	ds_read_b128 v[40:43], v101 offset:6144
	ds_read_b128 v[44:47], v101 offset:6160
	s_waitcnt lgkmcnt(2)
	v_pk_fma_f32 v[4:5], v[32:33], v[176:177], v[4:5]
	v_pk_fma_f32 v[6:7], v[34:35], v[178:179], v[6:7]
	v_pk_fma_f32 v[12:13], v[36:37], v[180:181], v[12:13]
	v_pk_fma_f32 v[14:15], v[38:39], v[182:183], v[14:15]
	v_pk_fma_f32 v[142:143], v[24:25], v[176:177], v[142:143]
	v_pk_fma_f32 v[138:139], v[26:27], v[178:179], v[138:139]
	v_pk_fma_f32 v[140:141], v[28:29], v[180:181], v[140:141]
	v_pk_fma_f32 v[136:137], v[30:31], v[182:183], v[136:137]
	v_pk_fma_f32 v[110:111], v[16:17], v[176:177], v[110:111]
	v_pk_fma_f32 v[106:107], v[18:19], v[178:179], v[106:107]
	v_pk_fma_f32 v[108:109], v[20:21], v[180:181], v[108:109]
	v_pk_fma_f32 v[104:105], v[22:23], v[182:183], v[104:105]
	s_waitcnt vmcnt(7)
	v_lshlrev_b32_e32 v186, 16, v156
	v_and_b32_e32 v187, 0xffff0000, v156
	v_lshlrev_b32_e32 v190, 16, v157
	v_and_b32_e32 v191, 0xffff0000, v157
	v_lshlrev_b32_e32 v192, 16, v158
	v_and_b32_e32 v193, 0xffff0000, v158
	v_lshlrev_b32_e32 v194, 16, v159
	v_and_b32_e32 v195, 0xffff0000, v159
	s_add_i32 s100, s37, 3
	s_cmp_ge_i32 s100, s36
	s_cselect_b32 s101, 1, 0
	s_cmp_lt_i32 s100, s31
	s_cselect_b32 s38, 1, 0
	s_and_b32 s101, s101, s38
	s_cbranch_scc1 .Lcv_ok3
	v_mov_b32_e32 v186, 0
	v_mov_b32_e32 v187, 0
	v_mov_b32_e32 v190, 0
	v_mov_b32_e32 v191, 0
	v_mov_b32_e32 v192, 0
	v_mov_b32_e32 v193, 0
	v_mov_b32_e32 v194, 0
	v_mov_b32_e32 v195, 0
.Lcv_ok3:
	s_add_i32 s38, s37, 11
	s_max_i32 s38, s38, s36
	s_min_i32 s38, s38, s39
	s_lshl_b32 s38, s38, 10
	s_add_u32 s0, s74, s38
	s_addc_u32 s1, s75, 0
	global_load_dwordx4 v[156:159], v100, s[0:1]
	ds_read_b128 v[48:51], v101 offset:8192
	ds_read_b128 v[52:55], v101 offset:8208
	s_waitcnt lgkmcnt(2)
	v_pk_fma_f32 v[4:5], v[40:41], v[186:187], v[4:5]
	v_pk_fma_f32 v[6:7], v[42:43], v[190:191], v[6:7]
	v_pk_fma_f32 v[12:13], v[44:45], v[192:193], v[12:13]
	v_pk_fma_f32 v[14:15], v[46:47], v[194:195], v[14:15]
	v_pk_fma_f32 v[142:143], v[32:33], v[186:187], v[142:143]
	v_pk_fma_f32 v[138:139], v[34:35], v[190:191], v[138:139]
	v_pk_fma_f32 v[140:141], v[36:37], v[192:193], v[140:141]
	v_pk_fma_f32 v[136:137], v[38:39], v[194:195], v[136:137]
	v_pk_fma_f32 v[110:111], v[24:25], v[186:187], v[110:111]
	v_pk_fma_f32 v[106:107], v[26:27], v[190:191], v[106:107]
	v_pk_fma_f32 v[108:109], v[28:29], v[192:193], v[108:109]
	v_pk_fma_f32 v[104:105], v[30:31], v[194:195], v[104:105]
	v_pk_fma_f32 v[94:95], v[16:17], v[186:187], v[94:95]
	v_pk_fma_f32 v[90:91], v[18:19], v[190:191], v[90:91]
	v_pk_fma_f32 v[92:93], v[20:21], v[192:193], v[92:93]
	v_pk_fma_f32 v[88:89], v[22:23], v[194:195], v[88:89]
	s_waitcnt vmcnt(7)
	v_lshlrev_b32_e32 v176, 16, v160
	v_and_b32_e32 v177, 0xffff0000, v160
	v_lshlrev_b32_e32 v178, 16, v161
	v_and_b32_e32 v179, 0xffff0000, v161
	v_lshlrev_b32_e32 v180, 16, v162
	v_and_b32_e32 v181, 0xffff0000, v162
	v_lshlrev_b32_e32 v182, 16, v163
	v_and_b32_e32 v183, 0xffff0000, v163
	s_add_i32 s100, s37, 4
	s_cmp_ge_i32 s100, s36
	s_cselect_b32 s101, 1, 0
	s_cmp_lt_i32 s100, s31
	s_cselect_b32 s38, 1, 0
	s_and_b32 s101, s101, s38
	s_cbranch_scc1 .Lcv_ok4
	v_mov_b32_e32 v176, 0
	v_mov_b32_e32 v177, 0
	v_mov_b32_e32 v178, 0
	v_mov_b32_e32 v179, 0
	v_mov_b32_e32 v180, 0
	v_mov_b32_e32 v181, 0
	v_mov_b32_e32 v182, 0
	v_mov_b32_e32 v183, 0
; DEV float lo_bf(unsigned u) { return __uint_as_float(u << 16); }
; DEV float hi_bf(unsigned u) { return __uint_as_float(u & 0xffff0000u); }
; DEV void conv_tile(const Params& p, int l, int tile, char* smem) {
;     ...
;   for (int s = 0; s < 40; ++s) {
;     const int rr = t0 - 15 + s;
;     u32x4 uv = {0u, 0u, 0u, 0u};
;     if (rr >= s_lo && rr < s_hi) uv = *(const u32x4*)(ZU + (size_t)rr * 512 + c0);
;     float u[8];
; #pragma unroll
;     for (int q = 0; q < 4; ++q) { u[2 * q] = lo_bf(uv[q]); u[2 * q + 1] = hi_bf(uv[q]); }
; #pragma unroll
;     for (int q = 7; q > 0; --q) { wk[q][0] = wk[q - 1][0]; wk[q][1] = wk[q - 1][1]; }
;     wk[0][0] = (f32x4){0.f, 0.f, 0.f, 0.f}; wk[0][1] = (f32x4){0.f, 0.f, 0.f, 0.f};
;     if (s <= 30) { wk[0][0] = *(const f32x4*)(wp + s * 512); wk[0][1] = *(const f32x4*)(wp + s * 512 + 4); }
; #pragma unroll
;     for (int t = 0; t < 8; ++t) {
; #pragma unroll
;       for (int j = 0; j < 4; ++j) { acc[t][j] += wk[t][0][j] * u[j]; acc[t][4 + j] += wk[t][1][j] * u[4 + j]; }
;     }
;   }
.Lcv_ok4:
	s_add_i32 s38, s37, 12
	s_max_i32 s38, s38, s36
	s_min_i32 s38, s38, s39
	s_lshl_b32 s38, s38, 10
	s_add_u32 s0, s74, s38
	s_addc_u32 s1, s75, 0
	global_load_dwordx4 v[160:163], v100, s[0:1]
	ds_read_b128 v[112:115], v101 offset:10240
	ds_read_b128 v[116:119], v101 offset:10256
	s_waitcnt lgkmcnt(2)
	v_pk_fma_f32 v[4:5], v[48:49], v[176:177], v[4:5]
	v_pk_fma_f32 v[6:7], v[50:51], v[178:179], v[6:7]
	v_pk_fma_f32 v[12:13], v[52:53], v[180:181], v[12:13]
	v_pk_fma_f32 v[14:15], v[54:55], v[182:183], v[14:15]
	v_pk_fma_f32 v[142:143], v[40:41], v[176:177], v[142:143]
	v_pk_fma_f32 v[138:139], v[42:43], v[178:179], v[138:139]
	v_pk_fma_f32 v[140:141], v[44:45], v[180:181], v[140:141]
	v_pk_fma_f32 v[136:137], v[46:47], v[182:183], v[136:137]
	v_pk_fma_f32 v[110:111], v[32:33], v[176:177], v[110:111]
	v_pk_fma_f32 v[106:107], v[34:35], v[178:179], v[106:107]
	v_pk_fma_f32 v[108:109], v[36:37], v[180:181], v[108:109]
	v_pk_fma_f32 v[104:105], v[38:39], v[182:183], v[104:105]
	v_pk_fma_f32 v[94:95], v[24:25], v[176:177], v[94:95]
	v_pk_fma_f32 v[90:91], v[26:27], v[178:179], v[90:91]
	v_pk_fma_f32 v[92:93], v[28:29], v[180:181], v[92:93]
	v_pk_fma_f32 v[88:89], v[30:31], v[182:183], v[88:89]
	v_pk_fma_f32 v[86:87], v[16:17], v[176:177], v[86:87]
	v_pk_fma_f32 v[82:83], v[18:19], v[178:179], v[82:83]
	v_pk_fma_f32 v[84:85], v[20:21], v[180:181], v[84:85]
	v_pk_fma_f32 v[80:81], v[22:23], v[182:183], v[80:81]
	s_waitcnt vmcnt(7)
	v_lshlrev_b32_e32 v186, 16, v164
	v_and_b32_e32 v187, 0xffff0000, v164
	v_lshlrev_b32_e32 v190, 16, v165
	v_and_b32_e32 v191, 0xffff0000, v165
	v_lshlrev_b32_e32 v192, 16, v166
	v_and_b32_e32 v193, 0xffff0000, v166
	v_lshlrev_b32_e32 v194, 16, v167
	v_and_b32_e32 v195, 0xffff0000, v167
	s_add_i32 s100, s37, 5
	s_cmp_ge_i32 s100, s36
	s_cselect_b32 s101, 1, 0
	s_cmp_lt_i32 s100, s31
	s_cselect_b32 s38, 1, 0
	s_and_b32 s101, s101, s38
	s_cbranch_scc1 .Lcv_ok5
	v_mov_b32_e32 v186, 0
	v_mov_b32_e32 v187, 0
	v_mov_b32_e32 v190, 0
	v_mov_b32_e32 v191, 0
	v_mov_b32_e32 v192, 0
	v_mov_b32_e32 v193, 0
	v_mov_b32_e32 v194, 0
	v_mov_b32_e32 v195, 0
.Lcv_ok5:
	s_add_i32 s38, s37, 13
	s_max_i32 s38, s38, s36
	s_min_i32 s38, s38, s39
	s_lshl_b32 s38, s38, 10
	s_add_u32 s0, s74, s38
	s_addc_u32 s1, s75, 0
	global_load_dwordx4 v[164:167], v100, s[0:1]
	ds_read_b128 v[120:123], v101 offset:12288
	ds_read_b128 v[124:127], v101 offset:12304
	s_waitcnt lgkmcnt(2)
	v_pk_fma_f32 v[4:5], v[112:113], v[186:187], v[4:5]
	v_pk_fma_f32 v[6:7], v[114:115], v[190:191], v[6:7]
	v_pk_fma_f32 v[12:13], v[116:117], v[192:193], v[12:13]
	v_pk_fma_f32 v[14:15], v[118:119], v[194:195], v[14:15]
	v_pk_fma_f32 v[142:143], v[48:49], v[186:187], v[142:143]
	v_pk_fma_f32 v[138:139], v[50:51], v[190:191], v[138:139]
	v_pk_fma_f32 v[140:141], v[52:53], v[192:193], v[140:141]
	v_pk_fma_f32 v[136:137], v[54:55], v[194:195], v[136:137]
	v_pk_fma_f32 v[110:111], v[40:41], v[186:187], v[110:111]
	v_pk_fma_f32 v[106:107], v[42:43], v[190:191], v[106:107]
	v_pk_fma_f32 v[108:109], v[44:45], v[192:193], v[108:109]
	v_pk_fma_f32 v[104:105], v[46:47], v[194:195], v[104:105]
	v_pk_fma_f32 v[94:95], v[32:33], v[186:187], v[94:95]
	v_pk_fma_f32 v[90:91], v[34:35], v[190:191], v[90:91]
	v_pk_fma_f32 v[92:93], v[36:37], v[192:193], v[92:93]
	v_pk_fma_f32 v[88:89], v[38:39], v[194:195], v[88:89]
	v_pk_fma_f32 v[86:87], v[24:25], v[186:187], v[86:87]
	v_pk_fma_f32 v[82:83], v[26:27], v[190:191], v[82:83]
	v_pk_fma_f32 v[84:85], v[28:29], v[192:193], v[84:85]
	v_pk_fma_f32 v[80:81], v[30:31], v[194:195], v[80:81]
	v_pk_fma_f32 v[78:79], v[16:17], v[186:187], v[78:79]
	v_pk_fma_f32 v[74:75], v[18:19], v[190:191], v[74:75]
	v_pk_fma_f32 v[76:77], v[20:21], v[192:193], v[76:77]
	v_pk_fma_f32 v[72:73], v[22:23], v[194:195], v[72:73]
	s_waitcnt vmcnt(7)
	v_lshlrev_b32_e32 v176, 16, v168
	v_and_b32_e32 v177, 0xffff0000, v168
	v_lshlrev_b32_e32 v178, 16, v169
	v_and_b32_e32 v179, 0xffff0000, v169
	v_lshlrev_b32_e32 v180, 16, v170
	v_and_b32_e32 v181, 0xffff0000, v170
	v_lshlrev_b32_e32 v182, 16, v171
	v_and_b32_e32 v183, 0xffff0000, v171
	s_add_i32 s100, s37, 6
	s_cmp_ge_i32 s100, s36
	s_cselect_b32 s101, 1, 0
	s_cmp_lt_i32 s100, s31
	s_cselect_b32 s38, 1, 0
	s_and_b32 s101, s101, s38
	s_cbranch_scc1 .Lcv_ok6
	v_mov_b32_e32 v176, 0
	v_mov_b32_e32 v177, 0
	v_mov_b32_e32 v178, 0
	v_mov_b32_e32 v179, 0
	v_mov_b32_e32 v180, 0
	v_mov_b32_e32 v181, 0
	v_mov_b32_e32 v182, 0
	v_mov_b32_e32 v183, 0
; DEV float lo_bf(unsigned u) { return __uint_as_float(u << 16); }
; DEV float hi_bf(unsigned u) { return __uint_as_float(u & 0xffff0000u); }
; DEV void conv_tile(const Params& p, int l, int tile, char* smem) {
;     ...
;   for (int s = 0; s < 40; ++s) {
;     const int rr = t0 - 15 + s;
;     u32x4 uv = {0u, 0u, 0u, 0u};
;     if (rr >= s_lo && rr < s_hi) uv = *(const u32x4*)(ZU + (size_t)rr * 512 + c0);
;     float u[8];
; #pragma unroll
;     for (int q = 0; q < 4; ++q) { u[2 * q] = lo_bf(uv[q]); u[2 * q + 1] = hi_bf(uv[q]); }
; #pragma unroll
;     for (int q = 7; q > 0; --q) { wk[q][0] = wk[q - 1][0]; wk[q][1] = wk[q - 1][1]; }
;     wk[0][0] = (f32x4){0.f, 0.f, 0.f, 0.f}; wk[0][1] = (f32x4){0.f, 0.f, 0.f, 0.f};
;     if (s <= 30) { wk[0][0] = *(const f32x4*)(wp + s * 512); wk[0][1] = *(const f32x4*)(wp + s * 512 + 4); }
; #pragma unroll
;     for (int t = 0; t < 8; ++t) {
; #pragma unroll
;       for (int j = 0; j < 4; ++j) { acc[t][j] += wk[t][0][j] * u[j]; acc[t][4 + j] += wk[t][1][j] * u[4 + j]; }
;     }
;   }
.Lcv_ok6:
	s_add_i32 s38, s37, 14
	s_max_i32 s38, s38, s36
	s_min_i32 s38, s38, s39
	s_lshl_b32 s38, s38, 10
	s_add_u32 s0, s74, s38
	s_addc_u32 s1, s75, 0
	global_load_dwordx4 v[168:171], v100, s[0:1]
	ds_read_b128 v[128:131], v101 offset:14336
	ds_read_b128 v[132:135], v101 offset:14352
	s_waitcnt lgkmcnt(2)
	v_pk_fma_f32 v[4:5], v[120:121], v[176:177], v[4:5]
	v_pk_fma_f32 v[6:7], v[122:123], v[178:179], v[6:7]
	v_pk_fma_f32 v[12:13], v[124:125], v[180:181], v[12:13]
	v_pk_fma_f32 v[14:15], v[126:127], v[182:183], v[14:15]
	v_pk_fma_f32 v[142:143], v[112:113], v[176:177], v[142:143]
	v_pk_fma_f32 v[138:139], v[114:115], v[178:179], v[138:139]
	v_pk_fma_f32 v[140:141], v[116:117], v[180:181], v[140:141]
	v_pk_fma_f32 v[136:137], v[118:119], v[182:183], v[136:137]
	v_pk_fma_f32 v[110:111], v[48:49], v[176:177], v[110:111]
	v_pk_fma_f32 v[106:107], v[50:51], v[178:179], v[106:107]
	v_pk_fma_f32 v[108:109], v[52:53], v[180:181], v[108:109]
	v_pk_fma_f32 v[104:105], v[54:55], v[182:183], v[104:105]
	v_pk_fma_f32 v[94:95], v[40:41], v[176:177], v[94:95]
	v_pk_fma_f32 v[90:91], v[42:43], v[178:179], v[90:91]
	v_pk_fma_f32 v[92:93], v[44:45], v[180:181], v[92:93]
	v_pk_fma_f32 v[88:89], v[46:47], v[182:183], v[88:89]
	v_pk_fma_f32 v[86:87], v[32:33], v[176:177], v[86:87]
	v_pk_fma_f32 v[82:83], v[34:35], v[178:179], v[82:83]
	v_pk_fma_f32 v[84:85], v[36:37], v[180:181], v[84:85]
	v_pk_fma_f32 v[80:81], v[38:39], v[182:183], v[80:81]
	v_pk_fma_f32 v[78:79], v[24:25], v[176:177], v[78:79]
	v_pk_fma_f32 v[74:75], v[26:27], v[178:179], v[74:75]
	v_pk_fma_f32 v[76:77], v[28:29], v[180:181], v[76:77]
	v_pk_fma_f32 v[72:73], v[30:31], v[182:183], v[72:73]
	v_pk_fma_f32 v[70:71], v[16:17], v[176:177], v[70:71]
	v_pk_fma_f32 v[66:67], v[18:19], v[178:179], v[66:67]
	v_pk_fma_f32 v[68:69], v[20:21], v[180:181], v[68:69]
	v_pk_fma_f32 v[64:65], v[22:23], v[182:183], v[64:65]
	s_waitcnt vmcnt(7)
	v_lshlrev_b32_e32 v186, 16, v172
	v_and_b32_e32 v187, 0xffff0000, v172
	v_lshlrev_b32_e32 v190, 16, v173
	v_and_b32_e32 v191, 0xffff0000, v173
	v_lshlrev_b32_e32 v192, 16, v174
	v_and_b32_e32 v193, 0xffff0000, v174
	v_lshlrev_b32_e32 v194, 16, v175
	v_and_b32_e32 v195, 0xffff0000, v175
	s_add_i32 s100, s37, 7
	s_cmp_ge_i32 s100, s36
	s_cselect_b32 s101, 1, 0
	s_cmp_lt_i32 s100, s31
	s_cselect_b32 s38, 1, 0
	s_and_b32 s101, s101, s38
	s_cbranch_scc1 .Lcv_ok7
	v_mov_b32_e32 v186, 0
	v_mov_b32_e32 v187, 0
	v_mov_b32_e32 v190, 0
	v_mov_b32_e32 v191, 0
	v_mov_b32_e32 v192, 0
	v_mov_b32_e32 v193, 0
	v_mov_b32_e32 v194, 0
	v_mov_b32_e32 v195, 0
.Lcv_ok7:
	s_add_i32 s38, s37, 15
	s_max_i32 s38, s38, s36
	s_min_i32 s38, s38, s39
	s_lshl_b32 s38, s38, 10
	s_add_u32 s0, s74, s38
	s_addc_u32 s1, s75, 0
	global_load_dwordx4 v[172:175], v100, s[0:1]
	ds_read_b128 v[0:3], v101 offset:16384
	ds_read_b128 v[8:11], v101 offset:16400
	s_waitcnt lgkmcnt(2)
	v_pk_fma_f32 v[4:5], v[128:129], v[186:187], v[4:5]
	v_pk_fma_f32 v[6:7], v[130:131], v[190:191], v[6:7]
	v_pk_fma_f32 v[12:13], v[132:133], v[192:193], v[12:13]
	v_pk_fma_f32 v[14:15], v[134:135], v[194:195], v[14:15]
	v_pk_fma_f32 v[142:143], v[120:121], v[186:187], v[142:143]
	v_pk_fma_f32 v[138:139], v[122:123], v[190:191], v[138:139]
	v_pk_fma_f32 v[140:141], v[124:125], v[192:193], v[140:141]
	v_pk_fma_f32 v[136:137], v[126:127], v[194:195], v[136:137]
	v_pk_fma_f32 v[110:111], v[112:113], v[186:187], v[110:111]
	v_pk_fma_f32 v[106:107], v[114:115], v[190:191], v[106:107]
	v_pk_fma_f32 v[108:109], v[116:117], v[192:193], v[108:109]
	v_pk_fma_f32 v[104:105], v[118:119], v[194:195], v[104:105]
	v_pk_fma_f32 v[94:95], v[48:49], v[186:187], v[94:95]
	v_pk_fma_f32 v[90:91], v[50:51], v[190:191], v[90:91]
	v_pk_fma_f32 v[92:93], v[52:53], v[192:193], v[92:93]
	v_pk_fma_f32 v[88:89], v[54:55], v[194:195], v[88:89]
	v_pk_fma_f32 v[86:87], v[40:41], v[186:187], v[86:87]
	v_pk_fma_f32 v[82:83], v[42:43], v[190:191], v[82:83]
	v_pk_fma_f32 v[84:85], v[44:45], v[192:193], v[84:85]
	v_pk_fma_f32 v[80:81], v[46:47], v[194:195], v[80:81]
	v_pk_fma_f32 v[78:79], v[32:33], v[186:187], v[78:79]
	v_pk_fma_f32 v[74:75], v[34:35], v[190:191], v[74:75]
	v_pk_fma_f32 v[76:77], v[36:37], v[192:193], v[76:77]
	v_pk_fma_f32 v[72:73], v[38:39], v[194:195], v[72:73]
	v_pk_fma_f32 v[70:71], v[24:25], v[186:187], v[70:71]
	v_pk_fma_f32 v[66:67], v[26:27], v[190:191], v[66:67]
	v_pk_fma_f32 v[68:69], v[28:29], v[192:193], v[68:69]
	v_pk_fma_f32 v[64:65], v[30:31], v[194:195], v[64:65]
	v_pk_fma_f32 v[62:63], v[16:17], v[186:187], v[62:63]
	v_pk_fma_f32 v[58:59], v[18:19], v[190:191], v[58:59]
	v_pk_fma_f32 v[60:61], v[20:21], v[192:193], v[60:61]
	v_pk_fma_f32 v[56:57], v[22:23], v[194:195], v[56:57]
	s_waitcnt vmcnt(7)
	v_lshlrev_b32_e32 v176, 16, v144
	v_and_b32_e32 v177, 0xffff0000, v144
	v_lshlrev_b32_e32 v178, 16, v145
	v_and_b32_e32 v179, 0xffff0000, v145
	v_lshlrev_b32_e32 v180, 16, v146
	v_and_b32_e32 v181, 0xffff0000, v146
	v_lshlrev_b32_e32 v182, 16, v147
	v_and_b32_e32 v183, 0xffff0000, v147
	s_add_i32 s100, s37, 8
	s_cmp_ge_i32 s100, s36
	s_cselect_b32 s101, 1, 0
	s_cmp_lt_i32 s100, s31
	s_cselect_b32 s38, 1, 0
	s_and_b32 s101, s101, s38
	s_cbranch_scc1 .Lcv_ok8
	v_mov_b32_e32 v176, 0
	v_mov_b32_e32 v177, 0
	v_mov_b32_e32 v178, 0
	v_mov_b32_e32 v179, 0
	v_mov_b32_e32 v180, 0
	v_mov_b32_e32 v181, 0
	v_mov_b32_e32 v182, 0
	v_mov_b32_e32 v183, 0
; DEV float lo_bf(unsigned u) { return __uint_as_float(u << 16); }
; DEV float hi_bf(unsigned u) { return __uint_as_float(u & 0xffff0000u); }
; DEV void conv_tile(const Params& p, int l, int tile, char* smem) {
;     ...
;   for (int s = 0; s < 40; ++s) {
;     const int rr = t0 - 15 + s;
;     u32x4 uv = {0u, 0u, 0u, 0u};
;     if (rr >= s_lo && rr < s_hi) uv = *(const u32x4*)(ZU + (size_t)rr * 512 + c0);
;     float u[8];
; #pragma unroll
;     for (int q = 0; q < 4; ++q) { u[2 * q] = lo_bf(uv[q]); u[2 * q + 1] = hi_bf(uv[q]); }
; #pragma unroll
;     for (int q = 7; q > 0; --q) { wk[q][0] = wk[q - 1][0]; wk[q][1] = wk[q - 1][1]; }
;     wk[0][0] = (f32x4){0.f, 0.f, 0.f, 0.f}; wk[0][1] = (f32x4){0.f, 0.f, 0.f, 0.f};
;     if (s <= 30) { wk[0][0] = *(const f32x4*)(wp + s * 512); wk[0][1] = *(const f32x4*)(wp + s * 512 + 4); }
; #pragma unroll
;     for (int t = 0; t < 8; ++t) {
; #pragma unroll
;       for (int j = 0; j < 4; ++j) { acc[t][j] += wk[t][0][j] * u[j]; acc[t][4 + j] += wk[t][1][j] * u[4 + j]; }
;     }
;   }
.Lcv_ok8:
	s_add_i32 s38, s37, 16
	s_max_i32 s38, s38, s36
	s_min_i32 s38, s38, s39
	s_lshl_b32 s38, s38, 10
	s_add_u32 s0, s74, s38
	s_addc_u32 s1, s75, 0
	global_load_dwordx4 v[144:147], v100, s[0:1]
	ds_read_b128 v[16:19], v101 offset:18432
	ds_read_b128 v[20:23], v101 offset:18448
	s_waitcnt lgkmcnt(2)
	v_pk_fma_f32 v[4:5], v[0:1], v[176:177], v[4:5]
	v_pk_fma_f32 v[6:7], v[2:3], v[178:179], v[6:7]
	v_pk_fma_f32 v[12:13], v[8:9], v[180:181], v[12:13]
	v_pk_fma_f32 v[14:15], v[10:11], v[182:183], v[14:15]
	v_pk_fma_f32 v[142:143], v[128:129], v[176:177], v[142:143]
	v_pk_fma_f32 v[138:139], v[130:131], v[178:179], v[138:139]
	v_pk_fma_f32 v[140:141], v[132:133], v[180:181], v[140:141]
	v_pk_fma_f32 v[136:137], v[134:135], v[182:183], v[136:137]
	v_pk_fma_f32 v[110:111], v[120:121], v[176:177], v[110:111]
	v_pk_fma_f32 v[106:107], v[122:123], v[178:179], v[106:107]
	v_pk_fma_f32 v[108:109], v[124:125], v[180:181], v[108:109]
	v_pk_fma_f32 v[104:105], v[126:127], v[182:183], v[104:105]
	v_pk_fma_f32 v[94:95], v[112:113], v[176:177], v[94:95]
	v_pk_fma_f32 v[90:91], v[114:115], v[178:179], v[90:91]
	v_pk_fma_f32 v[92:93], v[116:117], v[180:181], v[92:93]
	v_pk_fma_f32 v[88:89], v[118:119], v[182:183], v[88:89]
	v_pk_fma_f32 v[86:87], v[48:49], v[176:177], v[86:87]
	v_pk_fma_f32 v[82:83], v[50:51], v[178:179], v[82:83]
	v_pk_fma_f32 v[84:85], v[52:53], v[180:181], v[84:85]
	v_pk_fma_f32 v[80:81], v[54:55], v[182:183], v[80:81]
	v_pk_fma_f32 v[78:79], v[40:41], v[176:177], v[78:79]
	v_pk_fma_f32 v[74:75], v[42:43], v[178:179], v[74:75]
	v_pk_fma_f32 v[76:77], v[44:45], v[180:181], v[76:77]
	v_pk_fma_f32 v[72:73], v[46:47], v[182:183], v[72:73]
	v_pk_fma_f32 v[70:71], v[32:33], v[176:177], v[70:71]
	v_pk_fma_f32 v[66:67], v[34:35], v[178:179], v[66:67]
	v_pk_fma_f32 v[68:69], v[36:37], v[180:181], v[68:69]
	v_pk_fma_f32 v[64:65], v[38:39], v[182:183], v[64:65]
	v_pk_fma_f32 v[62:63], v[24:25], v[176:177], v[62:63]
	v_pk_fma_f32 v[58:59], v[26:27], v[178:179], v[58:59]
	v_pk_fma_f32 v[60:61], v[28:29], v[180:181], v[60:61]
	v_pk_fma_f32 v[56:57], v[30:31], v[182:183], v[56:57]
	s_waitcnt vmcnt(7)
	v_lshlrev_b32_e32 v186, 16, v148
	v_and_b32_e32 v187, 0xffff0000, v148
	v_lshlrev_b32_e32 v190, 16, v149
	v_and_b32_e32 v191, 0xffff0000, v149
	v_lshlrev_b32_e32 v192, 16, v150
	v_and_b32_e32 v193, 0xffff0000, v150
	v_lshlrev_b32_e32 v194, 16, v151
	v_and_b32_e32 v195, 0xffff0000, v151
	s_add_i32 s100, s37, 9
	s_cmp_ge_i32 s100, s36
	s_cselect_b32 s101, 1, 0
	s_cmp_lt_i32 s100, s31
	s_cselect_b32 s38, 1, 0
	s_and_b32 s101, s101, s38
	s_cbranch_scc1 .Lcv_ok9
	v_mov_b32_e32 v186, 0
	v_mov_b32_e32 v187, 0
	v_mov_b32_e32 v190, 0
	v_mov_b32_e32 v191, 0
	v_mov_b32_e32 v192, 0
	v_mov_b32_e32 v193, 0
	v_mov_b32_e32 v194, 0
	v_mov_b32_e32 v195, 0
.Lcv_ok9:
	s_add_i32 s38, s37, 17
	s_max_i32 s38, s38, s36
	s_min_i32 s38, s38, s39
	s_lshl_b32 s38, s38, 10
	s_add_u32 s0, s74, s38
	s_addc_u32 s1, s75, 0
	global_load_dwordx4 v[148:151], v100, s[0:1]
	ds_read_b128 v[24:27], v101 offset:20480
	ds_read_b128 v[28:31], v101 offset:20496
	s_waitcnt lgkmcnt(2)
	v_pk_fma_f32 v[4:5], v[16:17], v[186:187], v[4:5]
	v_pk_fma_f32 v[6:7], v[18:19], v[190:191], v[6:7]
	v_pk_fma_f32 v[12:13], v[20:21], v[192:193], v[12:13]
	v_pk_fma_f32 v[14:15], v[22:23], v[194:195], v[14:15]
	v_pk_fma_f32 v[142:143], v[0:1], v[186:187], v[142:143]
	v_pk_fma_f32 v[138:139], v[2:3], v[190:191], v[138:139]
	v_pk_fma_f32 v[140:141], v[8:9], v[192:193], v[140:141]
	v_pk_fma_f32 v[136:137], v[10:11], v[194:195], v[136:137]
	v_pk_fma_f32 v[110:111], v[128:129], v[186:187], v[110:111]
	v_pk_fma_f32 v[106:107], v[130:131], v[190:191], v[106:107]
	v_pk_fma_f32 v[108:109], v[132:133], v[192:193], v[108:109]
	v_pk_fma_f32 v[104:105], v[134:135], v[194:195], v[104:105]
	v_pk_fma_f32 v[94:95], v[120:121], v[186:187], v[94:95]
	v_pk_fma_f32 v[90:91], v[122:123], v[190:191], v[90:91]
	v_pk_fma_f32 v[92:93], v[124:125], v[192:193], v[92:93]
	v_pk_fma_f32 v[88:89], v[126:127], v[194:195], v[88:89]
	v_pk_fma_f32 v[86:87], v[112:113], v[186:187], v[86:87]
	v_pk_fma_f32 v[82:83], v[114:115], v[190:191], v[82:83]
	v_pk_fma_f32 v[84:85], v[116:117], v[192:193], v[84:85]
	v_pk_fma_f32 v[80:81], v[118:119], v[194:195], v[80:81]
	v_pk_fma_f32 v[78:79], v[48:49], v[186:187], v[78:79]
	v_pk_fma_f32 v[74:75], v[50:51], v[190:191], v[74:75]
	v_pk_fma_f32 v[76:77], v[52:53], v[192:193], v[76:77]
	v_pk_fma_f32 v[72:73], v[54:55], v[194:195], v[72:73]
	v_pk_fma_f32 v[70:71], v[40:41], v[186:187], v[70:71]
	v_pk_fma_f32 v[66:67], v[42:43], v[190:191], v[66:67]
	v_pk_fma_f32 v[68:69], v[44:45], v[192:193], v[68:69]
	v_pk_fma_f32 v[64:65], v[46:47], v[194:195], v[64:65]
	v_pk_fma_f32 v[62:63], v[32:33], v[186:187], v[62:63]
	v_pk_fma_f32 v[58:59], v[34:35], v[190:191], v[58:59]
	v_pk_fma_f32 v[60:61], v[36:37], v[192:193], v[60:61]
	v_pk_fma_f32 v[56:57], v[38:39], v[194:195], v[56:57]
	s_waitcnt vmcnt(7)
	v_lshlrev_b32_e32 v176, 16, v152
	v_and_b32_e32 v177, 0xffff0000, v152
	v_lshlrev_b32_e32 v178, 16, v153
	v_and_b32_e32 v179, 0xffff0000, v153
	v_lshlrev_b32_e32 v180, 16, v154
	v_and_b32_e32 v181, 0xffff0000, v154
	v_lshlrev_b32_e32 v182, 16, v155
	v_and_b32_e32 v183, 0xffff0000, v155
	s_add_i32 s100, s37, 10
	s_cmp_ge_i32 s100, s36
	s_cselect_b32 s101, 1, 0
	s_cmp_lt_i32 s100, s31
	s_cselect_b32 s38, 1, 0
	s_and_b32 s101, s101, s38
	s_cbranch_scc1 .Lcv_ok10
	v_mov_b32_e32 v176, 0
	v_mov_b32_e32 v177, 0
	v_mov_b32_e32 v178, 0
	v_mov_b32_e32 v179, 0
	v_mov_b32_e32 v180, 0
	v_mov_b32_e32 v181, 0
	v_mov_b32_e32 v182, 0
	v_mov_b32_e32 v183, 0
; DEV float lo_bf(unsigned u) { return __uint_as_float(u << 16); }
; DEV float hi_bf(unsigned u) { return __uint_as_float(u & 0xffff0000u); }
; DEV void conv_tile(const Params& p, int l, int tile, char* smem) {
;     ...
;   for (int s = 0; s < 40; ++s) {
;     const int rr = t0 - 15 + s;
;     u32x4 uv = {0u, 0u, 0u, 0u};
;     if (rr >= s_lo && rr < s_hi) uv = *(const u32x4*)(ZU + (size_t)rr * 512 + c0);
;     float u[8];
; #pragma unroll
;     for (int q = 0; q < 4; ++q) { u[2 * q] = lo_bf(uv[q]); u[2 * q + 1] = hi_bf(uv[q]); }
; #pragma unroll
;     for (int q = 7; q > 0; --q) { wk[q][0] = wk[q - 1][0]; wk[q][1] = wk[q - 1][1]; }
;     wk[0][0] = (f32x4){0.f, 0.f, 0.f, 0.f}; wk[0][1] = (f32x4){0.f, 0.f, 0.f, 0.f};
;     if (s <= 30) { wk[0][0] = *(const f32x4*)(wp + s * 512); wk[0][1] = *(const f32x4*)(wp + s * 512 + 4); }
; #pragma unroll
;     for (int t = 0; t < 8; ++t) {
; #pragma unroll
;       for (int j = 0; j < 4; ++j) { acc[t][j] += wk[t][0][j] * u[j]; acc[t][4 + j] += wk[t][1][j] * u[4 + j]; }
;     }
;   }
.Lcv_ok10:
	s_add_i32 s38, s37, 18
	s_max_i32 s38, s38, s36
	s_min_i32 s38, s38, s39
	s_lshl_b32 s38, s38, 10
	s_add_u32 s0, s74, s38
	s_addc_u32 s1, s75, 0
	global_load_dwordx4 v[152:155], v100, s[0:1]
	ds_read_b128 v[32:35], v101 offset:22528
	ds_read_b128 v[36:39], v101 offset:22544
	s_waitcnt lgkmcnt(2)
	v_pk_fma_f32 v[4:5], v[24:25], v[176:177], v[4:5]
	v_pk_fma_f32 v[6:7], v[26:27], v[178:179], v[6:7]
	v_pk_fma_f32 v[12:13], v[28:29], v[180:181], v[12:13]
	v_pk_fma_f32 v[14:15], v[30:31], v[182:183], v[14:15]
	v_pk_fma_f32 v[142:143], v[16:17], v[176:177], v[142:143]
	v_pk_fma_f32 v[138:139], v[18:19], v[178:179], v[138:139]
	v_pk_fma_f32 v[140:141], v[20:21], v[180:181], v[140:141]
	v_pk_fma_f32 v[136:137], v[22:23], v[182:183], v[136:137]
	v_pk_fma_f32 v[110:111], v[0:1], v[176:177], v[110:111]
	v_pk_fma_f32 v[106:107], v[2:3], v[178:179], v[106:107]
	v_pk_fma_f32 v[108:109], v[8:9], v[180:181], v[108:109]
	v_pk_fma_f32 v[104:105], v[10:11], v[182:183], v[104:105]
	v_pk_fma_f32 v[94:95], v[128:129], v[176:177], v[94:95]
	v_pk_fma_f32 v[90:91], v[130:131], v[178:179], v[90:91]
	v_pk_fma_f32 v[92:93], v[132:133], v[180:181], v[92:93]
	v_pk_fma_f32 v[88:89], v[134:135], v[182:183], v[88:89]
	v_pk_fma_f32 v[86:87], v[120:121], v[176:177], v[86:87]
	v_pk_fma_f32 v[82:83], v[122:123], v[178:179], v[82:83]
	v_pk_fma_f32 v[84:85], v[124:125], v[180:181], v[84:85]
	v_pk_fma_f32 v[80:81], v[126:127], v[182:183], v[80:81]
	v_pk_fma_f32 v[78:79], v[112:113], v[176:177], v[78:79]
	v_pk_fma_f32 v[74:75], v[114:115], v[178:179], v[74:75]
	v_pk_fma_f32 v[76:77], v[116:117], v[180:181], v[76:77]
	v_pk_fma_f32 v[72:73], v[118:119], v[182:183], v[72:73]
	v_pk_fma_f32 v[70:71], v[48:49], v[176:177], v[70:71]
	v_pk_fma_f32 v[66:67], v[50:51], v[178:179], v[66:67]
	v_pk_fma_f32 v[68:69], v[52:53], v[180:181], v[68:69]
	v_pk_fma_f32 v[64:65], v[54:55], v[182:183], v[64:65]
	v_pk_fma_f32 v[62:63], v[40:41], v[176:177], v[62:63]
	v_pk_fma_f32 v[58:59], v[42:43], v[178:179], v[58:59]
	v_pk_fma_f32 v[60:61], v[44:45], v[180:181], v[60:61]
	v_pk_fma_f32 v[56:57], v[46:47], v[182:183], v[56:57]
	s_waitcnt vmcnt(7)
	v_lshlrev_b32_e32 v186, 16, v156
	v_and_b32_e32 v187, 0xffff0000, v156
	v_lshlrev_b32_e32 v190, 16, v157
	v_and_b32_e32 v191, 0xffff0000, v157
	v_lshlrev_b32_e32 v192, 16, v158
	v_and_b32_e32 v193, 0xffff0000, v158
	v_lshlrev_b32_e32 v194, 16, v159
	v_and_b32_e32 v195, 0xffff0000, v159
	s_add_i32 s100, s37, 11
	s_cmp_ge_i32 s100, s36
	s_cselect_b32 s101, 1, 0
	s_cmp_lt_i32 s100, s31
	s_cselect_b32 s38, 1, 0
	s_and_b32 s101, s101, s38
	s_cbranch_scc1 .Lcv_ok11
	v_mov_b32_e32 v186, 0
	v_mov_b32_e32 v187, 0
	v_mov_b32_e32 v190, 0
	v_mov_b32_e32 v191, 0
	v_mov_b32_e32 v192, 0
	v_mov_b32_e32 v193, 0
	v_mov_b32_e32 v194, 0
	v_mov_b32_e32 v195, 0
.Lcv_ok11:
	s_add_i32 s38, s37, 19
	s_max_i32 s38, s38, s36
	s_min_i32 s38, s38, s39
	s_lshl_b32 s38, s38, 10
	s_add_u32 s0, s74, s38
	s_addc_u32 s1, s75, 0
	global_load_dwordx4 v[156:159], v100, s[0:1]
	ds_read_b128 v[40:43], v101 offset:24576
	ds_read_b128 v[44:47], v101 offset:24592
	s_waitcnt lgkmcnt(2)
	v_pk_fma_f32 v[4:5], v[32:33], v[186:187], v[4:5]
	v_pk_fma_f32 v[6:7], v[34:35], v[190:191], v[6:7]
	v_pk_fma_f32 v[12:13], v[36:37], v[192:193], v[12:13]
	v_pk_fma_f32 v[14:15], v[38:39], v[194:195], v[14:15]
	v_pk_fma_f32 v[142:143], v[24:25], v[186:187], v[142:143]
	v_pk_fma_f32 v[138:139], v[26:27], v[190:191], v[138:139]
	v_pk_fma_f32 v[140:141], v[28:29], v[192:193], v[140:141]
	v_pk_fma_f32 v[136:137], v[30:31], v[194:195], v[136:137]
	v_pk_fma_f32 v[110:111], v[16:17], v[186:187], v[110:111]
	v_pk_fma_f32 v[106:107], v[18:19], v[190:191], v[106:107]
	v_pk_fma_f32 v[108:109], v[20:21], v[192:193], v[108:109]
	v_pk_fma_f32 v[104:105], v[22:23], v[194:195], v[104:105]
	v_pk_fma_f32 v[94:95], v[0:1], v[186:187], v[94:95]
	v_pk_fma_f32 v[90:91], v[2:3], v[190:191], v[90:91]
	v_pk_fma_f32 v[92:93], v[8:9], v[192:193], v[92:93]
	v_pk_fma_f32 v[88:89], v[10:11], v[194:195], v[88:89]
	v_pk_fma_f32 v[86:87], v[128:129], v[186:187], v[86:87]
	v_pk_fma_f32 v[82:83], v[130:131], v[190:191], v[82:83]
	v_pk_fma_f32 v[84:85], v[132:133], v[192:193], v[84:85]
	v_pk_fma_f32 v[80:81], v[134:135], v[194:195], v[80:81]
	v_pk_fma_f32 v[78:79], v[120:121], v[186:187], v[78:79]
	v_pk_fma_f32 v[74:75], v[122:123], v[190:191], v[74:75]
	v_pk_fma_f32 v[76:77], v[124:125], v[192:193], v[76:77]
	v_pk_fma_f32 v[72:73], v[126:127], v[194:195], v[72:73]
	v_pk_fma_f32 v[70:71], v[112:113], v[186:187], v[70:71]
	v_pk_fma_f32 v[66:67], v[114:115], v[190:191], v[66:67]
	v_pk_fma_f32 v[68:69], v[116:117], v[192:193], v[68:69]
	v_pk_fma_f32 v[64:65], v[118:119], v[194:195], v[64:65]
	v_pk_fma_f32 v[62:63], v[48:49], v[186:187], v[62:63]
	v_pk_fma_f32 v[58:59], v[50:51], v[190:191], v[58:59]
	v_pk_fma_f32 v[60:61], v[52:53], v[192:193], v[60:61]
	v_pk_fma_f32 v[56:57], v[54:55], v[194:195], v[56:57]
	s_waitcnt vmcnt(7)
	v_lshlrev_b32_e32 v176, 16, v160
	v_and_b32_e32 v177, 0xffff0000, v160
	v_lshlrev_b32_e32 v178, 16, v161
	v_and_b32_e32 v179, 0xffff0000, v161
	v_lshlrev_b32_e32 v180, 16, v162
	v_and_b32_e32 v181, 0xffff0000, v162
	v_lshlrev_b32_e32 v182, 16, v163
	v_and_b32_e32 v183, 0xffff0000, v163
	s_add_i32 s100, s37, 12
	s_cmp_ge_i32 s100, s36
	s_cselect_b32 s101, 1, 0
	s_cmp_lt_i32 s100, s31
	s_cselect_b32 s38, 1, 0
	s_and_b32 s101, s101, s38
	s_cbranch_scc1 .Lcv_ok12
	v_mov_b32_e32 v176, 0
	v_mov_b32_e32 v177, 0
	v_mov_b32_e32 v178, 0
	v_mov_b32_e32 v179, 0
	v_mov_b32_e32 v180, 0
	v_mov_b32_e32 v181, 0
	v_mov_b32_e32 v182, 0
	v_mov_b32_e32 v183, 0
; DEV float lo_bf(unsigned u) { return __uint_as_float(u << 16); }
; DEV float hi_bf(unsigned u) { return __uint_as_float(u & 0xffff0000u); }
; DEV void conv_tile(const Params& p, int l, int tile, char* smem) {
;     ...
;   for (int s = 0; s < 40; ++s) {
;     const int rr = t0 - 15 + s;
;     u32x4 uv = {0u, 0u, 0u, 0u};
;     if (rr >= s_lo && rr < s_hi) uv = *(const u32x4*)(ZU + (size_t)rr * 512 + c0);
;     float u[8];
; #pragma unroll
;     for (int q = 0; q < 4; ++q) { u[2 * q] = lo_bf(uv[q]); u[2 * q + 1] = hi_bf(uv[q]); }
; #pragma unroll
;     for (int q = 7; q > 0; --q) { wk[q][0] = wk[q - 1][0]; wk[q][1] = wk[q - 1][1]; }
;     wk[0][0] = (f32x4){0.f, 0.f, 0.f, 0.f}; wk[0][1] = (f32x4){0.f, 0.f, 0.f, 0.f};
;     if (s <= 30) { wk[0][0] = *(const f32x4*)(wp + s * 512); wk[0][1] = *(const f32x4*)(wp + s * 512 + 4); }
; #pragma unroll
;     for (int t = 0; t < 8; ++t) {
; #pragma unroll
;       for (int j = 0; j < 4; ++j) { acc[t][j] += wk[t][0][j] * u[j]; acc[t][4 + j] += wk[t][1][j] * u[4 + j]; }
;     }
;   }
.Lcv_ok12:
	s_add_i32 s38, s37, 20
	s_max_i32 s38, s38, s36
	s_min_i32 s38, s38, s39
	s_lshl_b32 s38, s38, 10
	s_add_u32 s0, s74, s38
	s_addc_u32 s1, s75, 0
	global_load_dwordx4 v[160:163], v100, s[0:1]
	ds_read_b128 v[48:51], v101 offset:26624
	ds_read_b128 v[52:55], v101 offset:26640
	s_waitcnt lgkmcnt(2)
	v_pk_fma_f32 v[4:5], v[40:41], v[176:177], v[4:5]
	v_pk_fma_f32 v[6:7], v[42:43], v[178:179], v[6:7]
	v_pk_fma_f32 v[12:13], v[44:45], v[180:181], v[12:13]
	v_pk_fma_f32 v[14:15], v[46:47], v[182:183], v[14:15]
	v_pk_fma_f32 v[142:143], v[32:33], v[176:177], v[142:143]
	v_pk_fma_f32 v[138:139], v[34:35], v[178:179], v[138:139]
	v_pk_fma_f32 v[140:141], v[36:37], v[180:181], v[140:141]
	v_pk_fma_f32 v[136:137], v[38:39], v[182:183], v[136:137]
	v_pk_fma_f32 v[110:111], v[24:25], v[176:177], v[110:111]
	v_pk_fma_f32 v[106:107], v[26:27], v[178:179], v[106:107]
	v_pk_fma_f32 v[108:109], v[28:29], v[180:181], v[108:109]
	v_pk_fma_f32 v[104:105], v[30:31], v[182:183], v[104:105]
	v_pk_fma_f32 v[94:95], v[16:17], v[176:177], v[94:95]
	v_pk_fma_f32 v[90:91], v[18:19], v[178:179], v[90:91]
	v_pk_fma_f32 v[92:93], v[20:21], v[180:181], v[92:93]
	v_pk_fma_f32 v[88:89], v[22:23], v[182:183], v[88:89]
	v_pk_fma_f32 v[86:87], v[0:1], v[176:177], v[86:87]
	v_pk_fma_f32 v[82:83], v[2:3], v[178:179], v[82:83]
	v_pk_fma_f32 v[84:85], v[8:9], v[180:181], v[84:85]
	v_pk_fma_f32 v[80:81], v[10:11], v[182:183], v[80:81]
	v_pk_fma_f32 v[78:79], v[128:129], v[176:177], v[78:79]
	v_pk_fma_f32 v[74:75], v[130:131], v[178:179], v[74:75]
	v_pk_fma_f32 v[76:77], v[132:133], v[180:181], v[76:77]
	v_pk_fma_f32 v[72:73], v[134:135], v[182:183], v[72:73]
	v_pk_fma_f32 v[70:71], v[120:121], v[176:177], v[70:71]
	v_pk_fma_f32 v[66:67], v[122:123], v[178:179], v[66:67]
	v_pk_fma_f32 v[68:69], v[124:125], v[180:181], v[68:69]
	v_pk_fma_f32 v[64:65], v[126:127], v[182:183], v[64:65]
	v_pk_fma_f32 v[62:63], v[112:113], v[176:177], v[62:63]
	v_pk_fma_f32 v[58:59], v[114:115], v[178:179], v[58:59]
	v_pk_fma_f32 v[60:61], v[116:117], v[180:181], v[60:61]
	v_pk_fma_f32 v[56:57], v[118:119], v[182:183], v[56:57]
	s_waitcnt vmcnt(7)
	v_lshlrev_b32_e32 v186, 16, v164
	v_and_b32_e32 v187, 0xffff0000, v164
	v_lshlrev_b32_e32 v190, 16, v165
	v_and_b32_e32 v191, 0xffff0000, v165
	v_lshlrev_b32_e32 v192, 16, v166
	v_and_b32_e32 v193, 0xffff0000, v166
	v_lshlrev_b32_e32 v194, 16, v167
	v_and_b32_e32 v195, 0xffff0000, v167
	s_add_i32 s100, s37, 13
	s_cmp_ge_i32 s100, s36
	s_cselect_b32 s101, 1, 0
	s_cmp_lt_i32 s100, s31
	s_cselect_b32 s38, 1, 0
	s_and_b32 s101, s101, s38
	s_cbranch_scc1 .Lcv_ok13
	v_mov_b32_e32 v186, 0
	v_mov_b32_e32 v187, 0
	v_mov_b32_e32 v190, 0
	v_mov_b32_e32 v191, 0
	v_mov_b32_e32 v192, 0
	v_mov_b32_e32 v193, 0
	v_mov_b32_e32 v194, 0
	v_mov_b32_e32 v195, 0
.Lcv_ok13:
	s_add_i32 s38, s37, 21
	s_max_i32 s38, s38, s36
	s_min_i32 s38, s38, s39
	s_lshl_b32 s38, s38, 10
	s_add_u32 s0, s74, s38
	s_addc_u32 s1, s75, 0
	global_load_dwordx4 v[164:167], v100, s[0:1]
	ds_read_b128 v[112:115], v101 offset:28672
	ds_read_b128 v[116:119], v101 offset:28688
	s_waitcnt lgkmcnt(2)
	v_pk_fma_f32 v[4:5], v[48:49], v[186:187], v[4:5]
	v_pk_fma_f32 v[6:7], v[50:51], v[190:191], v[6:7]
	v_pk_fma_f32 v[12:13], v[52:53], v[192:193], v[12:13]
	v_pk_fma_f32 v[14:15], v[54:55], v[194:195], v[14:15]
	v_pk_fma_f32 v[142:143], v[40:41], v[186:187], v[142:143]
	v_pk_fma_f32 v[138:139], v[42:43], v[190:191], v[138:139]
	v_pk_fma_f32 v[140:141], v[44:45], v[192:193], v[140:141]
	v_pk_fma_f32 v[136:137], v[46:47], v[194:195], v[136:137]
	v_pk_fma_f32 v[110:111], v[32:33], v[186:187], v[110:111]
	v_pk_fma_f32 v[106:107], v[34:35], v[190:191], v[106:107]
	v_pk_fma_f32 v[108:109], v[36:37], v[192:193], v[108:109]
	v_pk_fma_f32 v[104:105], v[38:39], v[194:195], v[104:105]
	v_pk_fma_f32 v[94:95], v[24:25], v[186:187], v[94:95]
	v_pk_fma_f32 v[90:91], v[26:27], v[190:191], v[90:91]
	v_pk_fma_f32 v[92:93], v[28:29], v[192:193], v[92:93]
	v_pk_fma_f32 v[88:89], v[30:31], v[194:195], v[88:89]
	v_pk_fma_f32 v[86:87], v[16:17], v[186:187], v[86:87]
	v_pk_fma_f32 v[82:83], v[18:19], v[190:191], v[82:83]
	v_pk_fma_f32 v[84:85], v[20:21], v[192:193], v[84:85]
	v_pk_fma_f32 v[80:81], v[22:23], v[194:195], v[80:81]
	v_pk_fma_f32 v[78:79], v[0:1], v[186:187], v[78:79]
	v_pk_fma_f32 v[74:75], v[2:3], v[190:191], v[74:75]
	v_pk_fma_f32 v[76:77], v[8:9], v[192:193], v[76:77]
	v_pk_fma_f32 v[72:73], v[10:11], v[194:195], v[72:73]
	v_pk_fma_f32 v[70:71], v[128:129], v[186:187], v[70:71]
	v_pk_fma_f32 v[66:67], v[130:131], v[190:191], v[66:67]
	v_pk_fma_f32 v[68:69], v[132:133], v[192:193], v[68:69]
	v_pk_fma_f32 v[64:65], v[134:135], v[194:195], v[64:65]
	v_pk_fma_f32 v[62:63], v[120:121], v[186:187], v[62:63]
	v_pk_fma_f32 v[58:59], v[122:123], v[190:191], v[58:59]
	v_pk_fma_f32 v[60:61], v[124:125], v[192:193], v[60:61]
	v_pk_fma_f32 v[56:57], v[126:127], v[194:195], v[56:57]
	s_waitcnt vmcnt(7)
	v_lshlrev_b32_e32 v176, 16, v168
	v_and_b32_e32 v177, 0xffff0000, v168
	v_lshlrev_b32_e32 v178, 16, v169
	v_and_b32_e32 v179, 0xffff0000, v169
	v_lshlrev_b32_e32 v180, 16, v170
	v_and_b32_e32 v181, 0xffff0000, v170
	v_lshlrev_b32_e32 v182, 16, v171
	v_and_b32_e32 v183, 0xffff0000, v171
	s_add_i32 s100, s37, 14
	s_cmp_ge_i32 s100, s36
	s_cselect_b32 s101, 1, 0
	s_cmp_lt_i32 s100, s31
	s_cselect_b32 s38, 1, 0
	s_and_b32 s101, s101, s38
	s_cbranch_scc1 .Lcv_ok14
	v_mov_b32_e32 v176, 0
	v_mov_b32_e32 v177, 0
	v_mov_b32_e32 v178, 0
	v_mov_b32_e32 v179, 0
	v_mov_b32_e32 v180, 0
	v_mov_b32_e32 v181, 0
	v_mov_b32_e32 v182, 0
	v_mov_b32_e32 v183, 0
; DEV float lo_bf(unsigned u) { return __uint_as_float(u << 16); }
; DEV float hi_bf(unsigned u) { return __uint_as_float(u & 0xffff0000u); }
; DEV void conv_tile(const Params& p, int l, int tile, char* smem) {
;     ...
;   for (int s = 0; s < 40; ++s) {
;     const int rr = t0 - 15 + s;
;     u32x4 uv = {0u, 0u, 0u, 0u};
;     if (rr >= s_lo && rr < s_hi) uv = *(const u32x4*)(ZU + (size_t)rr * 512 + c0);
;     float u[8];
; #pragma unroll
;     for (int q = 0; q < 4; ++q) { u[2 * q] = lo_bf(uv[q]); u[2 * q + 1] = hi_bf(uv[q]); }
; #pragma unroll
;     for (int q = 7; q > 0; --q) { wk[q][0] = wk[q - 1][0]; wk[q][1] = wk[q - 1][1]; }
;     wk[0][0] = (f32x4){0.f, 0.f, 0.f, 0.f}; wk[0][1] = (f32x4){0.f, 0.f, 0.f, 0.f};
;     if (s <= 30) { wk[0][0] = *(const f32x4*)(wp + s * 512); wk[0][1] = *(const f32x4*)(wp + s * 512 + 4); }
; #pragma unroll
;     for (int t = 0; t < 8; ++t) {
; #pragma unroll
;       for (int j = 0; j < 4; ++j) { acc[t][j] += wk[t][0][j] * u[j]; acc[t][4 + j] += wk[t][1][j] * u[4 + j]; }
;     }
;   }
.Lcv_ok14:
	s_add_i32 s38, s37, 22
	s_max_i32 s38, s38, s36
	s_min_i32 s38, s38, s39
	s_lshl_b32 s38, s38, 10
	s_add_u32 s0, s74, s38
	s_addc_u32 s1, s75, 0
	global_load_dwordx4 v[168:171], v100, s[0:1]
	ds_read_b128 v[120:123], v101 offset:30720
	ds_read_b128 v[124:127], v101 offset:30736
	s_waitcnt lgkmcnt(2)
	v_pk_fma_f32 v[4:5], v[112:113], v[176:177], v[4:5]
	v_pk_fma_f32 v[6:7], v[114:115], v[178:179], v[6:7]
	v_pk_fma_f32 v[12:13], v[116:117], v[180:181], v[12:13]
	v_pk_fma_f32 v[14:15], v[118:119], v[182:183], v[14:15]
	v_pk_fma_f32 v[142:143], v[48:49], v[176:177], v[142:143]
	v_pk_fma_f32 v[138:139], v[50:51], v[178:179], v[138:139]
	v_pk_fma_f32 v[140:141], v[52:53], v[180:181], v[140:141]
	v_pk_fma_f32 v[136:137], v[54:55], v[182:183], v[136:137]
	v_pk_fma_f32 v[110:111], v[40:41], v[176:177], v[110:111]
	v_pk_fma_f32 v[106:107], v[42:43], v[178:179], v[106:107]
	v_pk_fma_f32 v[108:109], v[44:45], v[180:181], v[108:109]
	v_pk_fma_f32 v[104:105], v[46:47], v[182:183], v[104:105]
	v_pk_fma_f32 v[94:95], v[32:33], v[176:177], v[94:95]
	v_pk_fma_f32 v[90:91], v[34:35], v[178:179], v[90:91]
	v_pk_fma_f32 v[92:93], v[36:37], v[180:181], v[92:93]
	v_pk_fma_f32 v[88:89], v[38:39], v[182:183], v[88:89]
	v_pk_fma_f32 v[86:87], v[24:25], v[176:177], v[86:87]
	v_pk_fma_f32 v[82:83], v[26:27], v[178:179], v[82:83]
	v_pk_fma_f32 v[84:85], v[28:29], v[180:181], v[84:85]
	v_pk_fma_f32 v[80:81], v[30:31], v[182:183], v[80:81]
	v_pk_fma_f32 v[78:79], v[16:17], v[176:177], v[78:79]
	v_pk_fma_f32 v[74:75], v[18:19], v[178:179], v[74:75]
	v_pk_fma_f32 v[76:77], v[20:21], v[180:181], v[76:77]
	v_pk_fma_f32 v[72:73], v[22:23], v[182:183], v[72:73]
	v_pk_fma_f32 v[70:71], v[0:1], v[176:177], v[70:71]
	v_pk_fma_f32 v[66:67], v[2:3], v[178:179], v[66:67]
	v_pk_fma_f32 v[68:69], v[8:9], v[180:181], v[68:69]
	v_pk_fma_f32 v[64:65], v[10:11], v[182:183], v[64:65]
	v_pk_fma_f32 v[62:63], v[128:129], v[176:177], v[62:63]
	v_pk_fma_f32 v[58:59], v[130:131], v[178:179], v[58:59]
	v_pk_fma_f32 v[60:61], v[132:133], v[180:181], v[60:61]
	v_pk_fma_f32 v[56:57], v[134:135], v[182:183], v[56:57]
	s_waitcnt vmcnt(7)
	v_lshlrev_b32_e32 v186, 16, v172
	v_and_b32_e32 v187, 0xffff0000, v172
	v_lshlrev_b32_e32 v190, 16, v173
	v_and_b32_e32 v191, 0xffff0000, v173
	v_lshlrev_b32_e32 v192, 16, v174
	v_and_b32_e32 v193, 0xffff0000, v174
	v_lshlrev_b32_e32 v194, 16, v175
	v_and_b32_e32 v195, 0xffff0000, v175
	s_add_i32 s100, s37, 15
	s_cmp_ge_i32 s100, s36
	s_cselect_b32 s101, 1, 0
	s_cmp_lt_i32 s100, s31
	s_cselect_b32 s38, 1, 0
	s_and_b32 s101, s101, s38
	s_cbranch_scc1 .Lcv_ok15
	v_mov_b32_e32 v186, 0
	v_mov_b32_e32 v187, 0
	v_mov_b32_e32 v190, 0
	v_mov_b32_e32 v191, 0
	v_mov_b32_e32 v192, 0
	v_mov_b32_e32 v193, 0
	v_mov_b32_e32 v194, 0
	v_mov_b32_e32 v195, 0
.Lcv_ok15:
	s_add_i32 s38, s37, 23
	s_max_i32 s38, s38, s36
	s_min_i32 s38, s38, s39
	s_lshl_b32 s38, s38, 10
	s_add_u32 s0, s74, s38
	s_addc_u32 s1, s75, 0
	global_load_dwordx4 v[172:175], v100, s[0:1]
	ds_read_b128 v[128:131], v101 offset:32768
	ds_read_b128 v[132:135], v101 offset:32784
	s_waitcnt lgkmcnt(2)
	v_pk_fma_f32 v[4:5], v[120:121], v[186:187], v[4:5]
	v_pk_fma_f32 v[6:7], v[122:123], v[190:191], v[6:7]
	v_pk_fma_f32 v[12:13], v[124:125], v[192:193], v[12:13]
	v_pk_fma_f32 v[14:15], v[126:127], v[194:195], v[14:15]
	v_pk_fma_f32 v[142:143], v[112:113], v[186:187], v[142:143]
	v_pk_fma_f32 v[138:139], v[114:115], v[190:191], v[138:139]
	v_pk_fma_f32 v[140:141], v[116:117], v[192:193], v[140:141]
	v_pk_fma_f32 v[136:137], v[118:119], v[194:195], v[136:137]
	v_pk_fma_f32 v[110:111], v[48:49], v[186:187], v[110:111]
	v_pk_fma_f32 v[106:107], v[50:51], v[190:191], v[106:107]
	v_pk_fma_f32 v[108:109], v[52:53], v[192:193], v[108:109]
	v_pk_fma_f32 v[104:105], v[54:55], v[194:195], v[104:105]
	v_pk_fma_f32 v[94:95], v[40:41], v[186:187], v[94:95]
	v_pk_fma_f32 v[90:91], v[42:43], v[190:191], v[90:91]
	v_pk_fma_f32 v[92:93], v[44:45], v[192:193], v[92:93]
	v_pk_fma_f32 v[88:89], v[46:47], v[194:195], v[88:89]
	v_pk_fma_f32 v[86:87], v[32:33], v[186:187], v[86:87]
	v_pk_fma_f32 v[82:83], v[34:35], v[190:191], v[82:83]
	v_pk_fma_f32 v[84:85], v[36:37], v[192:193], v[84:85]
	v_pk_fma_f32 v[80:81], v[38:39], v[194:195], v[80:81]
	v_pk_fma_f32 v[78:79], v[24:25], v[186:187], v[78:79]
	v_pk_fma_f32 v[74:75], v[26:27], v[190:191], v[74:75]
	v_pk_fma_f32 v[76:77], v[28:29], v[192:193], v[76:77]
	v_pk_fma_f32 v[72:73], v[30:31], v[194:195], v[72:73]
	v_pk_fma_f32 v[70:71], v[16:17], v[186:187], v[70:71]
	v_pk_fma_f32 v[66:67], v[18:19], v[190:191], v[66:67]
	v_pk_fma_f32 v[68:69], v[20:21], v[192:193], v[68:69]
	v_pk_fma_f32 v[64:65], v[22:23], v[194:195], v[64:65]
	v_pk_fma_f32 v[62:63], v[0:1], v[186:187], v[62:63]
	v_pk_fma_f32 v[58:59], v[2:3], v[190:191], v[58:59]
	v_pk_fma_f32 v[60:61], v[8:9], v[192:193], v[60:61]
	v_pk_fma_f32 v[56:57], v[10:11], v[194:195], v[56:57]
	s_waitcnt vmcnt(7)
	v_lshlrev_b32_e32 v176, 16, v144
	v_and_b32_e32 v177, 0xffff0000, v144
	v_lshlrev_b32_e32 v178, 16, v145
	v_and_b32_e32 v179, 0xffff0000, v145
	v_lshlrev_b32_e32 v180, 16, v146
	v_and_b32_e32 v181, 0xffff0000, v146
	v_lshlrev_b32_e32 v182, 16, v147
	v_and_b32_e32 v183, 0xffff0000, v147
	s_add_i32 s100, s37, 16
	s_cmp_ge_i32 s100, s36
	s_cselect_b32 s101, 1, 0
	s_cmp_lt_i32 s100, s31
	s_cselect_b32 s38, 1, 0
	s_and_b32 s101, s101, s38
	s_cbranch_scc1 .Lcv_ok16
	v_mov_b32_e32 v176, 0
	v_mov_b32_e32 v177, 0
	v_mov_b32_e32 v178, 0
	v_mov_b32_e32 v179, 0
	v_mov_b32_e32 v180, 0
	v_mov_b32_e32 v181, 0
	v_mov_b32_e32 v182, 0
	v_mov_b32_e32 v183, 0
; DEV float lo_bf(unsigned u) { return __uint_as_float(u << 16); }
; DEV float hi_bf(unsigned u) { return __uint_as_float(u & 0xffff0000u); }
; DEV void conv_tile(const Params& p, int l, int tile, char* smem) {
;     ...
;   for (int s = 0; s < 40; ++s) {
;     const int rr = t0 - 15 + s;
;     u32x4 uv = {0u, 0u, 0u, 0u};
;     if (rr >= s_lo && rr < s_hi) uv = *(const u32x4*)(ZU + (size_t)rr * 512 + c0);
;     float u[8];
; #pragma unroll
;     for (int q = 0; q < 4; ++q) { u[2 * q] = lo_bf(uv[q]); u[2 * q + 1] = hi_bf(uv[q]); }
; #pragma unroll
;     for (int q = 7; q > 0; --q) { wk[q][0] = wk[q - 1][0]; wk[q][1] = wk[q - 1][1]; }
;     wk[0][0] = (f32x4){0.f, 0.f, 0.f, 0.f}; wk[0][1] = (f32x4){0.f, 0.f, 0.f, 0.f};
;     if (s <= 30) { wk[0][0] = *(const f32x4*)(wp + s * 512); wk[0][1] = *(const f32x4*)(wp + s * 512 + 4); }
; #pragma unroll
;     for (int t = 0; t < 8; ++t) {
; #pragma unroll
;       for (int j = 0; j < 4; ++j) { acc[t][j] += wk[t][0][j] * u[j]; acc[t][4 + j] += wk[t][1][j] * u[4 + j]; }
;     }
;   }
.Lcv_ok16:
	s_add_i32 s38, s37, 24
	s_max_i32 s38, s38, s36
	s_min_i32 s38, s38, s39
	s_lshl_b32 s38, s38, 10
	s_add_u32 s0, s74, s38
	s_addc_u32 s1, s75, 0
	global_load_dwordx4 v[144:147], v100, s[0:1]
	ds_read_b128 v[0:3], v101 offset:34816
	ds_read_b128 v[8:11], v101 offset:34832
	s_waitcnt lgkmcnt(2)
	v_pk_fma_f32 v[4:5], v[128:129], v[176:177], v[4:5]
	v_pk_fma_f32 v[6:7], v[130:131], v[178:179], v[6:7]
	v_pk_fma_f32 v[12:13], v[132:133], v[180:181], v[12:13]
	v_pk_fma_f32 v[14:15], v[134:135], v[182:183], v[14:15]
	v_pk_fma_f32 v[142:143], v[120:121], v[176:177], v[142:143]
	v_pk_fma_f32 v[138:139], v[122:123], v[178:179], v[138:139]
	v_pk_fma_f32 v[140:141], v[124:125], v[180:181], v[140:141]
	v_pk_fma_f32 v[136:137], v[126:127], v[182:183], v[136:137]
	v_pk_fma_f32 v[110:111], v[112:113], v[176:177], v[110:111]
	v_pk_fma_f32 v[106:107], v[114:115], v[178:179], v[106:107]
	v_pk_fma_f32 v[108:109], v[116:117], v[180:181], v[108:109]
	v_pk_fma_f32 v[104:105], v[118:119], v[182:183], v[104:105]
	v_pk_fma_f32 v[94:95], v[48:49], v[176:177], v[94:95]
	v_pk_fma_f32 v[90:91], v[50:51], v[178:179], v[90:91]
	v_pk_fma_f32 v[92:93], v[52:53], v[180:181], v[92:93]
	v_pk_fma_f32 v[88:89], v[54:55], v[182:183], v[88:89]
	v_pk_fma_f32 v[86:87], v[40:41], v[176:177], v[86:87]
	v_pk_fma_f32 v[82:83], v[42:43], v[178:179], v[82:83]
	v_pk_fma_f32 v[84:85], v[44:45], v[180:181], v[84:85]
	v_pk_fma_f32 v[80:81], v[46:47], v[182:183], v[80:81]
	v_pk_fma_f32 v[78:79], v[32:33], v[176:177], v[78:79]
	v_pk_fma_f32 v[74:75], v[34:35], v[178:179], v[74:75]
	v_pk_fma_f32 v[76:77], v[36:37], v[180:181], v[76:77]
	v_pk_fma_f32 v[72:73], v[38:39], v[182:183], v[72:73]
	v_pk_fma_f32 v[70:71], v[24:25], v[176:177], v[70:71]
	v_pk_fma_f32 v[66:67], v[26:27], v[178:179], v[66:67]
	v_pk_fma_f32 v[68:69], v[28:29], v[180:181], v[68:69]
	v_pk_fma_f32 v[64:65], v[30:31], v[182:183], v[64:65]
	v_pk_fma_f32 v[62:63], v[16:17], v[176:177], v[62:63]
	v_pk_fma_f32 v[58:59], v[18:19], v[178:179], v[58:59]
	v_pk_fma_f32 v[60:61], v[20:21], v[180:181], v[60:61]
	v_pk_fma_f32 v[56:57], v[22:23], v[182:183], v[56:57]
	s_waitcnt vmcnt(7)
	v_lshlrev_b32_e32 v186, 16, v148
	v_and_b32_e32 v187, 0xffff0000, v148
	v_lshlrev_b32_e32 v190, 16, v149
	v_and_b32_e32 v191, 0xffff0000, v149
	v_lshlrev_b32_e32 v192, 16, v150
	v_and_b32_e32 v193, 0xffff0000, v150
	v_lshlrev_b32_e32 v194, 16, v151
	v_and_b32_e32 v195, 0xffff0000, v151
	s_add_i32 s100, s37, 17
	s_cmp_ge_i32 s100, s36
	s_cselect_b32 s101, 1, 0
	s_cmp_lt_i32 s100, s31
	s_cselect_b32 s38, 1, 0
	s_and_b32 s101, s101, s38
	s_cbranch_scc1 .Lcv_ok17
	v_mov_b32_e32 v186, 0
	v_mov_b32_e32 v187, 0
	v_mov_b32_e32 v190, 0
	v_mov_b32_e32 v191, 0
	v_mov_b32_e32 v192, 0
	v_mov_b32_e32 v193, 0
	v_mov_b32_e32 v194, 0
	v_mov_b32_e32 v195, 0
.Lcv_ok17:
	s_add_i32 s38, s37, 25
	s_max_i32 s38, s38, s36
	s_min_i32 s38, s38, s39
	s_lshl_b32 s38, s38, 10
	s_add_u32 s0, s74, s38
	s_addc_u32 s1, s75, 0
	global_load_dwordx4 v[148:151], v100, s[0:1]
	ds_read_b128 v[16:19], v101 offset:36864
	ds_read_b128 v[20:23], v101 offset:36880
	s_waitcnt lgkmcnt(2)
	v_pk_fma_f32 v[4:5], v[0:1], v[186:187], v[4:5]
	v_pk_fma_f32 v[6:7], v[2:3], v[190:191], v[6:7]
	v_pk_fma_f32 v[12:13], v[8:9], v[192:193], v[12:13]
	v_pk_fma_f32 v[14:15], v[10:11], v[194:195], v[14:15]
	v_pk_fma_f32 v[142:143], v[128:129], v[186:187], v[142:143]
	v_pk_fma_f32 v[138:139], v[130:131], v[190:191], v[138:139]
	v_pk_fma_f32 v[140:141], v[132:133], v[192:193], v[140:141]
	v_pk_fma_f32 v[136:137], v[134:135], v[194:195], v[136:137]
	v_pk_fma_f32 v[110:111], v[120:121], v[186:187], v[110:111]
	v_pk_fma_f32 v[106:107], v[122:123], v[190:191], v[106:107]
	v_pk_fma_f32 v[108:109], v[124:125], v[192:193], v[108:109]
	v_pk_fma_f32 v[104:105], v[126:127], v[194:195], v[104:105]
	v_pk_fma_f32 v[94:95], v[112:113], v[186:187], v[94:95]
	v_pk_fma_f32 v[90:91], v[114:115], v[190:191], v[90:91]
	v_pk_fma_f32 v[92:93], v[116:117], v[192:193], v[92:93]
	v_pk_fma_f32 v[88:89], v[118:119], v[194:195], v[88:89]
	v_pk_fma_f32 v[86:87], v[48:49], v[186:187], v[86:87]
	v_pk_fma_f32 v[82:83], v[50:51], v[190:191], v[82:83]
	v_pk_fma_f32 v[84:85], v[52:53], v[192:193], v[84:85]
	v_pk_fma_f32 v[80:81], v[54:55], v[194:195], v[80:81]
	v_pk_fma_f32 v[78:79], v[40:41], v[186:187], v[78:79]
	v_pk_fma_f32 v[74:75], v[42:43], v[190:191], v[74:75]
	v_pk_fma_f32 v[76:77], v[44:45], v[192:193], v[76:77]
	v_pk_fma_f32 v[72:73], v[46:47], v[194:195], v[72:73]
	v_pk_fma_f32 v[70:71], v[32:33], v[186:187], v[70:71]
	v_pk_fma_f32 v[66:67], v[34:35], v[190:191], v[66:67]
	v_pk_fma_f32 v[68:69], v[36:37], v[192:193], v[68:69]
	v_pk_fma_f32 v[64:65], v[38:39], v[194:195], v[64:65]
	v_pk_fma_f32 v[62:63], v[24:25], v[186:187], v[62:63]
	v_pk_fma_f32 v[58:59], v[26:27], v[190:191], v[58:59]
	v_pk_fma_f32 v[60:61], v[28:29], v[192:193], v[60:61]
	v_pk_fma_f32 v[56:57], v[30:31], v[194:195], v[56:57]
	s_waitcnt vmcnt(7)
	v_lshlrev_b32_e32 v176, 16, v152
	v_and_b32_e32 v177, 0xffff0000, v152
	v_lshlrev_b32_e32 v178, 16, v153
	v_and_b32_e32 v179, 0xffff0000, v153
	v_lshlrev_b32_e32 v180, 16, v154
	v_and_b32_e32 v181, 0xffff0000, v154
	v_lshlrev_b32_e32 v182, 16, v155
	v_and_b32_e32 v183, 0xffff0000, v155
	s_add_i32 s100, s37, 18
	s_cmp_ge_i32 s100, s36
	s_cselect_b32 s101, 1, 0
	s_cmp_lt_i32 s100, s31
	s_cselect_b32 s38, 1, 0
	s_and_b32 s101, s101, s38
	s_cbranch_scc1 .Lcv_ok18
	v_mov_b32_e32 v176, 0
	v_mov_b32_e32 v177, 0
	v_mov_b32_e32 v178, 0
	v_mov_b32_e32 v179, 0
	v_mov_b32_e32 v180, 0
	v_mov_b32_e32 v181, 0
	v_mov_b32_e32 v182, 0
	v_mov_b32_e32 v183, 0
; DEV float lo_bf(unsigned u) { return __uint_as_float(u << 16); }
; DEV float hi_bf(unsigned u) { return __uint_as_float(u & 0xffff0000u); }
; DEV void conv_tile(const Params& p, int l, int tile, char* smem) {
;     ...
; #pragma unroll 4
;   for (int s = 0; s < 40; ++s) {
;     const int rr = t0 - 15 + s;
;     u32x4 uv = {0u, 0u, 0u, 0u};
;     if (rr >= s_lo && rr < s_hi) uv = *(const u32x4*)(ZU + (size_t)rr * 512 + c0);
;     float u[8];
; #pragma unroll
;     for (int q = 0; q < 4; ++q) { u[2 * q] = lo_bf(uv[q]); u[2 * q + 1] = hi_bf(uv[q]); }
; #pragma unroll
;     for (int q = 7; q > 0; --q) { wk[q][0] = wk[q - 1][0]; wk[q][1] = wk[q - 1][1]; }
;     wk[0][0] = (f32x4){0.f, 0.f, 0.f, 0.f}; wk[0][1] = (f32x4){0.f, 0.f, 0.f, 0.f};
;     if (s <= 30) { wk[0][0] = *(const f32x4*)(wp + s * 512); wk[0][1] = *(const f32x4*)(wp + s * 512 + 4); }
; #pragma unroll
;     for (int t = 0; t < 8; ++t) {
; #pragma unroll
;       for (int j = 0; j < 4; ++j) { acc[t][j] += wk[t][0][j] * u[j]; acc[t][4 + j] += wk[t][1][j] * u[4 + j]; }
;     }
;   }
.Lcv_ok18:
	s_add_i32 s38, s37, 26
	s_max_i32 s38, s38, s36
	s_min_i32 s38, s38, s39
	s_lshl_b32 s38, s38, 10
	s_add_u32 s0, s74, s38
	s_addc_u32 s1, s75, 0
	global_load_dwordx4 v[152:155], v100, s[0:1]
	ds_read_b128 v[24:27], v101 offset:38912
	ds_read_b128 v[28:31], v101 offset:38928
	s_waitcnt lgkmcnt(2)
	v_pk_fma_f32 v[4:5], v[16:17], v[176:177], v[4:5]
	v_pk_fma_f32 v[6:7], v[18:19], v[178:179], v[6:7]
	v_pk_fma_f32 v[12:13], v[20:21], v[180:181], v[12:13]
	v_pk_fma_f32 v[14:15], v[22:23], v[182:183], v[14:15]
	v_pk_fma_f32 v[142:143], v[0:1], v[176:177], v[142:143]
	v_pk_fma_f32 v[138:139], v[2:3], v[178:179], v[138:139]
	v_pk_fma_f32 v[140:141], v[8:9], v[180:181], v[140:141]
	v_pk_fma_f32 v[136:137], v[10:11], v[182:183], v[136:137]
	v_pk_fma_f32 v[110:111], v[128:129], v[176:177], v[110:111]
	v_pk_fma_f32 v[106:107], v[130:131], v[178:179], v[106:107]
	v_pk_fma_f32 v[108:109], v[132:133], v[180:181], v[108:109]
	v_pk_fma_f32 v[104:105], v[134:135], v[182:183], v[104:105]
	v_pk_fma_f32 v[94:95], v[120:121], v[176:177], v[94:95]
	v_pk_fma_f32 v[90:91], v[122:123], v[178:179], v[90:91]
	v_pk_fma_f32 v[92:93], v[124:125], v[180:181], v[92:93]
	v_pk_fma_f32 v[88:89], v[126:127], v[182:183], v[88:89]
	v_pk_fma_f32 v[86:87], v[112:113], v[176:177], v[86:87]
	v_pk_fma_f32 v[82:83], v[114:115], v[178:179], v[82:83]
	v_pk_fma_f32 v[84:85], v[116:117], v[180:181], v[84:85]
	v_pk_fma_f32 v[80:81], v[118:119], v[182:183], v[80:81]
	v_pk_fma_f32 v[78:79], v[48:49], v[176:177], v[78:79]
	v_pk_fma_f32 v[74:75], v[50:51], v[178:179], v[74:75]
	v_pk_fma_f32 v[76:77], v[52:53], v[180:181], v[76:77]
	v_pk_fma_f32 v[72:73], v[54:55], v[182:183], v[72:73]
	v_pk_fma_f32 v[70:71], v[40:41], v[176:177], v[70:71]
	v_pk_fma_f32 v[66:67], v[42:43], v[178:179], v[66:67]
	v_pk_fma_f32 v[68:69], v[44:45], v[180:181], v[68:69]
	v_pk_fma_f32 v[64:65], v[46:47], v[182:183], v[64:65]
	v_pk_fma_f32 v[62:63], v[32:33], v[176:177], v[62:63]
	v_pk_fma_f32 v[58:59], v[34:35], v[178:179], v[58:59]
	v_pk_fma_f32 v[60:61], v[36:37], v[180:181], v[60:61]
	v_pk_fma_f32 v[56:57], v[38:39], v[182:183], v[56:57]
	s_waitcnt vmcnt(7)
	v_lshlrev_b32_e32 v186, 16, v156
	v_and_b32_e32 v187, 0xffff0000, v156
	v_lshlrev_b32_e32 v190, 16, v157
	v_and_b32_e32 v191, 0xffff0000, v157
	v_lshlrev_b32_e32 v192, 16, v158
	v_and_b32_e32 v193, 0xffff0000, v158
	v_lshlrev_b32_e32 v194, 16, v159
	v_and_b32_e32 v195, 0xffff0000, v159
	s_add_i32 s100, s37, 19
	s_cmp_ge_i32 s100, s36
	s_cselect_b32 s101, 1, 0
	s_cmp_lt_i32 s100, s31
	s_cselect_b32 s38, 1, 0
	s_and_b32 s101, s101, s38
	s_cbranch_scc1 .Lcv_ok19
	v_mov_b32_e32 v186, 0
	v_mov_b32_e32 v187, 0
	v_mov_b32_e32 v190, 0
	v_mov_b32_e32 v191, 0
	v_mov_b32_e32 v192, 0
	v_mov_b32_e32 v193, 0
	v_mov_b32_e32 v194, 0
	v_mov_b32_e32 v195, 0
.Lcv_ok19:
	s_add_i32 s38, s37, 27
	s_max_i32 s38, s38, s36
	s_min_i32 s38, s38, s39
	s_lshl_b32 s38, s38, 10
	s_add_u32 s0, s74, s38
	s_addc_u32 s1, s75, 0
	global_load_dwordx4 v[156:159], v100, s[0:1]
	ds_read_b128 v[32:35], v101 offset:40960
	ds_read_b128 v[36:39], v101 offset:40976
	s_waitcnt lgkmcnt(2)
	v_pk_fma_f32 v[4:5], v[24:25], v[186:187], v[4:5]
	v_pk_fma_f32 v[6:7], v[26:27], v[190:191], v[6:7]
	v_pk_fma_f32 v[12:13], v[28:29], v[192:193], v[12:13]
	v_pk_fma_f32 v[14:15], v[30:31], v[194:195], v[14:15]
	v_pk_fma_f32 v[142:143], v[16:17], v[186:187], v[142:143]
	v_pk_fma_f32 v[138:139], v[18:19], v[190:191], v[138:139]
	v_pk_fma_f32 v[140:141], v[20:21], v[192:193], v[140:141]
	v_pk_fma_f32 v[136:137], v[22:23], v[194:195], v[136:137]
	v_pk_fma_f32 v[110:111], v[0:1], v[186:187], v[110:111]
	v_pk_fma_f32 v[106:107], v[2:3], v[190:191], v[106:107]
	v_pk_fma_f32 v[108:109], v[8:9], v[192:193], v[108:109]
	v_pk_fma_f32 v[104:105], v[10:11], v[194:195], v[104:105]
	v_pk_fma_f32 v[94:95], v[128:129], v[186:187], v[94:95]
	v_pk_fma_f32 v[90:91], v[130:131], v[190:191], v[90:91]
	v_pk_fma_f32 v[92:93], v[132:133], v[192:193], v[92:93]
	v_pk_fma_f32 v[88:89], v[134:135], v[194:195], v[88:89]
	v_pk_fma_f32 v[86:87], v[120:121], v[186:187], v[86:87]
	v_pk_fma_f32 v[82:83], v[122:123], v[190:191], v[82:83]
	v_pk_fma_f32 v[84:85], v[124:125], v[192:193], v[84:85]
	v_pk_fma_f32 v[80:81], v[126:127], v[194:195], v[80:81]
	v_pk_fma_f32 v[78:79], v[112:113], v[186:187], v[78:79]
	v_pk_fma_f32 v[74:75], v[114:115], v[190:191], v[74:75]
	v_pk_fma_f32 v[76:77], v[116:117], v[192:193], v[76:77]
	v_pk_fma_f32 v[72:73], v[118:119], v[194:195], v[72:73]
	v_pk_fma_f32 v[70:71], v[48:49], v[186:187], v[70:71]
	v_pk_fma_f32 v[66:67], v[50:51], v[190:191], v[66:67]
	v_pk_fma_f32 v[68:69], v[52:53], v[192:193], v[68:69]
	v_pk_fma_f32 v[64:65], v[54:55], v[194:195], v[64:65]
	v_pk_fma_f32 v[62:63], v[40:41], v[186:187], v[62:63]
	v_pk_fma_f32 v[58:59], v[42:43], v[190:191], v[58:59]
	v_pk_fma_f32 v[60:61], v[44:45], v[192:193], v[60:61]
	v_pk_fma_f32 v[56:57], v[46:47], v[194:195], v[56:57]
	s_waitcnt vmcnt(7)
	v_lshlrev_b32_e32 v176, 16, v160
	v_and_b32_e32 v177, 0xffff0000, v160
	v_lshlrev_b32_e32 v178, 16, v161
	v_and_b32_e32 v179, 0xffff0000, v161
	v_lshlrev_b32_e32 v180, 16, v162
	v_and_b32_e32 v181, 0xffff0000, v162
	v_lshlrev_b32_e32 v182, 16, v163
	v_and_b32_e32 v183, 0xffff0000, v163
	s_add_i32 s100, s37, 20
	s_cmp_ge_i32 s100, s36
	s_cselect_b32 s101, 1, 0
	s_cmp_lt_i32 s100, s31
	s_cselect_b32 s38, 1, 0
	s_and_b32 s101, s101, s38
	s_cbranch_scc1 .Lcv_ok20
	v_mov_b32_e32 v176, 0
	v_mov_b32_e32 v177, 0
	v_mov_b32_e32 v178, 0
	v_mov_b32_e32 v179, 0
	v_mov_b32_e32 v180, 0
	v_mov_b32_e32 v181, 0
	v_mov_b32_e32 v182, 0
	v_mov_b32_e32 v183, 0
; DEV float lo_bf(unsigned u) { return __uint_as_float(u << 16); }
; DEV float hi_bf(unsigned u) { return __uint_as_float(u & 0xffff0000u); }
; DEV void conv_tile(const Params& p, int l, int tile, char* smem) {
;     ...
; #pragma unroll 4
;   for (int s = 0; s < 40; ++s) {
;     const int rr = t0 - 15 + s;
;     u32x4 uv = {0u, 0u, 0u, 0u};
;     if (rr >= s_lo && rr < s_hi) uv = *(const u32x4*)(ZU + (size_t)rr * 512 + c0);
;     float u[8];
; #pragma unroll
;     for (int q = 0; q < 4; ++q) { u[2 * q] = lo_bf(uv[q]); u[2 * q + 1] = hi_bf(uv[q]); }
; #pragma unroll
;     for (int q = 7; q > 0; --q) { wk[q][0] = wk[q - 1][0]; wk[q][1] = wk[q - 1][1]; }
;     wk[0][0] = (f32x4){0.f, 0.f, 0.f, 0.f}; wk[0][1] = (f32x4){0.f, 0.f, 0.f, 0.f};
;     if (s <= 30) { wk[0][0] = *(const f32x4*)(wp + s * 512); wk[0][1] = *(const f32x4*)(wp + s * 512 + 4); }
; #pragma unroll
;     for (int t = 0; t < 8; ++t) {
; #pragma unroll
;       for (int j = 0; j < 4; ++j) { acc[t][j] += wk[t][0][j] * u[j]; acc[t][4 + j] += wk[t][1][j] * u[4 + j]; }
;     }
;   }
.Lcv_ok20:
	s_add_i32 s38, s37, 28
	s_max_i32 s38, s38, s36
	s_min_i32 s38, s38, s39
	s_lshl_b32 s38, s38, 10
	s_add_u32 s0, s74, s38
	s_addc_u32 s1, s75, 0
	global_load_dwordx4 v[160:163], v100, s[0:1]
	ds_read_b128 v[40:43], v101 offset:43008
	ds_read_b128 v[44:47], v101 offset:43024
	s_waitcnt lgkmcnt(2)
	v_pk_fma_f32 v[4:5], v[32:33], v[176:177], v[4:5]
	v_pk_fma_f32 v[6:7], v[34:35], v[178:179], v[6:7]
	v_pk_fma_f32 v[12:13], v[36:37], v[180:181], v[12:13]
	v_pk_fma_f32 v[14:15], v[38:39], v[182:183], v[14:15]
	v_pk_fma_f32 v[142:143], v[24:25], v[176:177], v[142:143]
	v_pk_fma_f32 v[138:139], v[26:27], v[178:179], v[138:139]
	v_pk_fma_f32 v[140:141], v[28:29], v[180:181], v[140:141]
	v_pk_fma_f32 v[136:137], v[30:31], v[182:183], v[136:137]
	v_pk_fma_f32 v[110:111], v[16:17], v[176:177], v[110:111]
	v_pk_fma_f32 v[106:107], v[18:19], v[178:179], v[106:107]
	v_pk_fma_f32 v[108:109], v[20:21], v[180:181], v[108:109]
	v_pk_fma_f32 v[104:105], v[22:23], v[182:183], v[104:105]
	v_pk_fma_f32 v[94:95], v[0:1], v[176:177], v[94:95]
	v_pk_fma_f32 v[90:91], v[2:3], v[178:179], v[90:91]
	v_pk_fma_f32 v[92:93], v[8:9], v[180:181], v[92:93]
	v_pk_fma_f32 v[88:89], v[10:11], v[182:183], v[88:89]
	v_pk_fma_f32 v[86:87], v[128:129], v[176:177], v[86:87]
	v_pk_fma_f32 v[82:83], v[130:131], v[178:179], v[82:83]
	v_pk_fma_f32 v[84:85], v[132:133], v[180:181], v[84:85]
	v_pk_fma_f32 v[80:81], v[134:135], v[182:183], v[80:81]
	v_pk_fma_f32 v[78:79], v[120:121], v[176:177], v[78:79]
	v_pk_fma_f32 v[74:75], v[122:123], v[178:179], v[74:75]
	v_pk_fma_f32 v[76:77], v[124:125], v[180:181], v[76:77]
	v_pk_fma_f32 v[72:73], v[126:127], v[182:183], v[72:73]
	v_pk_fma_f32 v[70:71], v[112:113], v[176:177], v[70:71]
	v_pk_fma_f32 v[66:67], v[114:115], v[178:179], v[66:67]
	v_pk_fma_f32 v[68:69], v[116:117], v[180:181], v[68:69]
	v_pk_fma_f32 v[64:65], v[118:119], v[182:183], v[64:65]
	v_pk_fma_f32 v[62:63], v[48:49], v[176:177], v[62:63]
	v_pk_fma_f32 v[58:59], v[50:51], v[178:179], v[58:59]
	v_pk_fma_f32 v[60:61], v[52:53], v[180:181], v[60:61]
	v_pk_fma_f32 v[56:57], v[54:55], v[182:183], v[56:57]
	s_waitcnt vmcnt(7)
	v_lshlrev_b32_e32 v186, 16, v164
	v_and_b32_e32 v187, 0xffff0000, v164
	v_lshlrev_b32_e32 v190, 16, v165
	v_and_b32_e32 v191, 0xffff0000, v165
	v_lshlrev_b32_e32 v192, 16, v166
	v_and_b32_e32 v193, 0xffff0000, v166
	v_lshlrev_b32_e32 v194, 16, v167
	v_and_b32_e32 v195, 0xffff0000, v167
	s_add_i32 s100, s37, 21
	s_cmp_ge_i32 s100, s36
	s_cselect_b32 s101, 1, 0
	s_cmp_lt_i32 s100, s31
	s_cselect_b32 s38, 1, 0
	s_and_b32 s101, s101, s38
	s_cbranch_scc1 .Lcv_ok21
	v_mov_b32_e32 v186, 0
	v_mov_b32_e32 v187, 0
	v_mov_b32_e32 v190, 0
	v_mov_b32_e32 v191, 0
	v_mov_b32_e32 v192, 0
	v_mov_b32_e32 v193, 0
	v_mov_b32_e32 v194, 0
	v_mov_b32_e32 v195, 0
.Lcv_ok21:
	s_add_i32 s38, s37, 29
	s_max_i32 s38, s38, s36
	s_min_i32 s38, s38, s39
	s_lshl_b32 s38, s38, 10
	s_add_u32 s0, s74, s38
	s_addc_u32 s1, s75, 0
	global_load_dwordx4 v[164:167], v100, s[0:1]
	ds_read_b128 v[48:51], v101 offset:45056
	ds_read_b128 v[52:55], v101 offset:45072
	s_waitcnt lgkmcnt(2)
	v_pk_fma_f32 v[4:5], v[40:41], v[186:187], v[4:5]
	v_pk_fma_f32 v[6:7], v[42:43], v[190:191], v[6:7]
	v_pk_fma_f32 v[12:13], v[44:45], v[192:193], v[12:13]
	v_pk_fma_f32 v[14:15], v[46:47], v[194:195], v[14:15]
	v_pk_fma_f32 v[142:143], v[32:33], v[186:187], v[142:143]
	v_pk_fma_f32 v[138:139], v[34:35], v[190:191], v[138:139]
	v_pk_fma_f32 v[140:141], v[36:37], v[192:193], v[140:141]
	v_pk_fma_f32 v[136:137], v[38:39], v[194:195], v[136:137]
	v_pk_fma_f32 v[110:111], v[24:25], v[186:187], v[110:111]
	v_pk_fma_f32 v[106:107], v[26:27], v[190:191], v[106:107]
	v_pk_fma_f32 v[108:109], v[28:29], v[192:193], v[108:109]
	v_pk_fma_f32 v[104:105], v[30:31], v[194:195], v[104:105]
	v_pk_fma_f32 v[94:95], v[16:17], v[186:187], v[94:95]
	v_pk_fma_f32 v[90:91], v[18:19], v[190:191], v[90:91]
	v_pk_fma_f32 v[92:93], v[20:21], v[192:193], v[92:93]
	v_pk_fma_f32 v[88:89], v[22:23], v[194:195], v[88:89]
	v_pk_fma_f32 v[86:87], v[0:1], v[186:187], v[86:87]
	v_pk_fma_f32 v[82:83], v[2:3], v[190:191], v[82:83]
	v_pk_fma_f32 v[84:85], v[8:9], v[192:193], v[84:85]
	v_pk_fma_f32 v[80:81], v[10:11], v[194:195], v[80:81]
	v_pk_fma_f32 v[78:79], v[128:129], v[186:187], v[78:79]
	v_pk_fma_f32 v[74:75], v[130:131], v[190:191], v[74:75]
	v_pk_fma_f32 v[76:77], v[132:133], v[192:193], v[76:77]
	v_pk_fma_f32 v[72:73], v[134:135], v[194:195], v[72:73]
	v_pk_fma_f32 v[70:71], v[120:121], v[186:187], v[70:71]
	v_pk_fma_f32 v[66:67], v[122:123], v[190:191], v[66:67]
	v_pk_fma_f32 v[68:69], v[124:125], v[192:193], v[68:69]
	v_pk_fma_f32 v[64:65], v[126:127], v[194:195], v[64:65]
	v_pk_fma_f32 v[62:63], v[112:113], v[186:187], v[62:63]
	v_pk_fma_f32 v[58:59], v[114:115], v[190:191], v[58:59]
	v_pk_fma_f32 v[60:61], v[116:117], v[192:193], v[60:61]
	v_pk_fma_f32 v[56:57], v[118:119], v[194:195], v[56:57]
	s_waitcnt vmcnt(7)
	v_lshlrev_b32_e32 v176, 16, v168
	v_and_b32_e32 v177, 0xffff0000, v168
	v_lshlrev_b32_e32 v178, 16, v169
	v_and_b32_e32 v179, 0xffff0000, v169
	v_lshlrev_b32_e32 v180, 16, v170
	v_and_b32_e32 v181, 0xffff0000, v170
	v_lshlrev_b32_e32 v182, 16, v171
	v_and_b32_e32 v183, 0xffff0000, v171
	s_add_i32 s100, s37, 22
	s_cmp_ge_i32 s100, s36
	s_cselect_b32 s101, 1, 0
	s_cmp_lt_i32 s100, s31
	s_cselect_b32 s38, 1, 0
	s_and_b32 s101, s101, s38
	s_cbranch_scc1 .Lcv_ok22
	v_mov_b32_e32 v176, 0
	v_mov_b32_e32 v177, 0
	v_mov_b32_e32 v178, 0
	v_mov_b32_e32 v179, 0
	v_mov_b32_e32 v180, 0
	v_mov_b32_e32 v181, 0
	v_mov_b32_e32 v182, 0
	v_mov_b32_e32 v183, 0
; DEV float lo_bf(unsigned u) { return __uint_as_float(u << 16); }
; DEV float hi_bf(unsigned u) { return __uint_as_float(u & 0xffff0000u); }
; DEV void conv_tile(const Params& p, int l, int tile, char* smem) {
;     ...
; #pragma unroll 4
;   for (int s = 0; s < 40; ++s) {
;     const int rr = t0 - 15 + s;
;     u32x4 uv = {0u, 0u, 0u, 0u};
;     if (rr >= s_lo && rr < s_hi) uv = *(const u32x4*)(ZU + (size_t)rr * 512 + c0);
;     float u[8];
; #pragma unroll
;     for (int q = 0; q < 4; ++q) { u[2 * q] = lo_bf(uv[q]); u[2 * q + 1] = hi_bf(uv[q]); }
; #pragma unroll
;     for (int q = 7; q > 0; --q) { wk[q][0] = wk[q - 1][0]; wk[q][1] = wk[q - 1][1]; }
;     wk[0][0] = (f32x4){0.f, 0.f, 0.f, 0.f}; wk[0][1] = (f32x4){0.f, 0.f, 0.f, 0.f};
;     if (s <= 30) { wk[0][0] = *(const f32x4*)(wp + s * 512); wk[0][1] = *(const f32x4*)(wp + s * 512 + 4); }
; #pragma unroll
;     for (int t = 0; t < 8; ++t) {
; #pragma unroll
;       for (int j = 0; j < 4; ++j) { acc[t][j] += wk[t][0][j] * u[j]; acc[t][4 + j] += wk[t][1][j] * u[4 + j]; }
;     }
;   }
.Lcv_ok22:
	s_add_i32 s38, s37, 30
	s_max_i32 s38, s38, s36
	s_min_i32 s38, s38, s39
	s_lshl_b32 s38, s38, 10
	s_add_u32 s0, s74, s38
	s_addc_u32 s1, s75, 0
	global_load_dwordx4 v[168:171], v100, s[0:1]
	ds_read_b128 v[112:115], v101 offset:47104
	ds_read_b128 v[116:119], v101 offset:47120
	s_waitcnt lgkmcnt(2)
	v_pk_fma_f32 v[4:5], v[48:49], v[176:177], v[4:5]
	v_pk_fma_f32 v[6:7], v[50:51], v[178:179], v[6:7]
	v_pk_fma_f32 v[12:13], v[52:53], v[180:181], v[12:13]
	v_pk_fma_f32 v[14:15], v[54:55], v[182:183], v[14:15]
	v_pk_fma_f32 v[142:143], v[40:41], v[176:177], v[142:143]
	v_pk_fma_f32 v[138:139], v[42:43], v[178:179], v[138:139]
	v_pk_fma_f32 v[140:141], v[44:45], v[180:181], v[140:141]
	v_pk_fma_f32 v[136:137], v[46:47], v[182:183], v[136:137]
	v_pk_fma_f32 v[110:111], v[32:33], v[176:177], v[110:111]
	v_pk_fma_f32 v[106:107], v[34:35], v[178:179], v[106:107]
	v_pk_fma_f32 v[108:109], v[36:37], v[180:181], v[108:109]
	v_pk_fma_f32 v[104:105], v[38:39], v[182:183], v[104:105]
	v_pk_fma_f32 v[94:95], v[24:25], v[176:177], v[94:95]
	v_pk_fma_f32 v[90:91], v[26:27], v[178:179], v[90:91]
	v_pk_fma_f32 v[92:93], v[28:29], v[180:181], v[92:93]
	v_pk_fma_f32 v[88:89], v[30:31], v[182:183], v[88:89]
	v_pk_fma_f32 v[86:87], v[16:17], v[176:177], v[86:87]
	v_pk_fma_f32 v[82:83], v[18:19], v[178:179], v[82:83]
	v_pk_fma_f32 v[84:85], v[20:21], v[180:181], v[84:85]
	v_pk_fma_f32 v[80:81], v[22:23], v[182:183], v[80:81]
	v_pk_fma_f32 v[78:79], v[0:1], v[176:177], v[78:79]
	v_pk_fma_f32 v[74:75], v[2:3], v[178:179], v[74:75]
	v_pk_fma_f32 v[76:77], v[8:9], v[180:181], v[76:77]
	v_pk_fma_f32 v[72:73], v[10:11], v[182:183], v[72:73]
	v_pk_fma_f32 v[70:71], v[128:129], v[176:177], v[70:71]
	v_pk_fma_f32 v[66:67], v[130:131], v[178:179], v[66:67]
	v_pk_fma_f32 v[68:69], v[132:133], v[180:181], v[68:69]
	v_pk_fma_f32 v[64:65], v[134:135], v[182:183], v[64:65]
	v_pk_fma_f32 v[62:63], v[120:121], v[176:177], v[62:63]
	v_pk_fma_f32 v[58:59], v[122:123], v[178:179], v[58:59]
	v_pk_fma_f32 v[60:61], v[124:125], v[180:181], v[60:61]
	v_pk_fma_f32 v[56:57], v[126:127], v[182:183], v[56:57]
	s_waitcnt vmcnt(7)
	v_lshlrev_b32_e32 v186, 16, v172
	v_and_b32_e32 v187, 0xffff0000, v172
	v_lshlrev_b32_e32 v190, 16, v173
	v_and_b32_e32 v191, 0xffff0000, v173
	v_lshlrev_b32_e32 v192, 16, v174
	v_and_b32_e32 v193, 0xffff0000, v174
	v_lshlrev_b32_e32 v194, 16, v175
	v_and_b32_e32 v195, 0xffff0000, v175
	s_add_i32 s100, s37, 23
	s_cmp_ge_i32 s100, s36
	s_cselect_b32 s101, 1, 0
	s_cmp_lt_i32 s100, s31
	s_cselect_b32 s38, 1, 0
	s_and_b32 s101, s101, s38
	s_cbranch_scc1 .Lcv_ok23
	v_mov_b32_e32 v186, 0
	v_mov_b32_e32 v187, 0
	v_mov_b32_e32 v190, 0
	v_mov_b32_e32 v191, 0
	v_mov_b32_e32 v192, 0
	v_mov_b32_e32 v193, 0
	v_mov_b32_e32 v194, 0
	v_mov_b32_e32 v195, 0
.Lcv_ok23:
	s_add_i32 s38, s37, 31
	s_max_i32 s38, s38, s36
	s_min_i32 s38, s38, s39
	s_lshl_b32 s38, s38, 10
	s_add_u32 s0, s74, s38
	s_addc_u32 s1, s75, 0
	global_load_dwordx4 v[172:175], v100, s[0:1]
	ds_read_b128 v[120:123], v101 offset:49152
	ds_read_b128 v[124:127], v101 offset:49168
	s_waitcnt lgkmcnt(2)
	v_pk_fma_f32 v[4:5], v[112:113], v[186:187], v[4:5]
	v_pk_fma_f32 v[6:7], v[114:115], v[190:191], v[6:7]
	v_pk_fma_f32 v[12:13], v[116:117], v[192:193], v[12:13]
	v_pk_fma_f32 v[14:15], v[118:119], v[194:195], v[14:15]
	v_pk_fma_f32 v[142:143], v[48:49], v[186:187], v[142:143]
	v_pk_fma_f32 v[138:139], v[50:51], v[190:191], v[138:139]
	v_pk_fma_f32 v[140:141], v[52:53], v[192:193], v[140:141]
	v_pk_fma_f32 v[136:137], v[54:55], v[194:195], v[136:137]
	v_pk_fma_f32 v[110:111], v[40:41], v[186:187], v[110:111]
	v_pk_fma_f32 v[106:107], v[42:43], v[190:191], v[106:107]
	v_pk_fma_f32 v[108:109], v[44:45], v[192:193], v[108:109]
	v_pk_fma_f32 v[104:105], v[46:47], v[194:195], v[104:105]
	v_pk_fma_f32 v[94:95], v[32:33], v[186:187], v[94:95]
	v_pk_fma_f32 v[90:91], v[34:35], v[190:191], v[90:91]
	v_pk_fma_f32 v[92:93], v[36:37], v[192:193], v[92:93]
	v_pk_fma_f32 v[88:89], v[38:39], v[194:195], v[88:89]
	v_pk_fma_f32 v[86:87], v[24:25], v[186:187], v[86:87]
	v_pk_fma_f32 v[82:83], v[26:27], v[190:191], v[82:83]
	v_pk_fma_f32 v[84:85], v[28:29], v[192:193], v[84:85]
	v_pk_fma_f32 v[80:81], v[30:31], v[194:195], v[80:81]
	v_pk_fma_f32 v[78:79], v[16:17], v[186:187], v[78:79]
	v_pk_fma_f32 v[74:75], v[18:19], v[190:191], v[74:75]
	v_pk_fma_f32 v[76:77], v[20:21], v[192:193], v[76:77]
	v_pk_fma_f32 v[72:73], v[22:23], v[194:195], v[72:73]
	v_pk_fma_f32 v[70:71], v[0:1], v[186:187], v[70:71]
	v_pk_fma_f32 v[66:67], v[2:3], v[190:191], v[66:67]
	v_pk_fma_f32 v[68:69], v[8:9], v[192:193], v[68:69]
	v_pk_fma_f32 v[64:65], v[10:11], v[194:195], v[64:65]
	v_pk_fma_f32 v[62:63], v[128:129], v[186:187], v[62:63]
	v_pk_fma_f32 v[58:59], v[130:131], v[190:191], v[58:59]
	v_pk_fma_f32 v[60:61], v[132:133], v[192:193], v[60:61]
	v_pk_fma_f32 v[56:57], v[134:135], v[194:195], v[56:57]
	s_waitcnt vmcnt(7)
	v_lshlrev_b32_e32 v176, 16, v144
	v_and_b32_e32 v177, 0xffff0000, v144
	v_lshlrev_b32_e32 v178, 16, v145
	v_and_b32_e32 v179, 0xffff0000, v145
	v_lshlrev_b32_e32 v180, 16, v146
	v_and_b32_e32 v181, 0xffff0000, v146
	v_lshlrev_b32_e32 v182, 16, v147
	v_and_b32_e32 v183, 0xffff0000, v147
	s_add_i32 s100, s37, 24
	s_cmp_ge_i32 s100, s36
	s_cselect_b32 s101, 1, 0
	s_cmp_lt_i32 s100, s31
	s_cselect_b32 s38, 1, 0
	s_and_b32 s101, s101, s38
	s_cbranch_scc1 .Lcv_ok24
	v_mov_b32_e32 v176, 0
	v_mov_b32_e32 v177, 0
	v_mov_b32_e32 v178, 0
	v_mov_b32_e32 v179, 0
	v_mov_b32_e32 v180, 0
	v_mov_b32_e32 v181, 0
	v_mov_b32_e32 v182, 0
	v_mov_b32_e32 v183, 0
; DEV float lo_bf(unsigned u) { return __uint_as_float(u << 16); }
; DEV float hi_bf(unsigned u) { return __uint_as_float(u & 0xffff0000u); }
; DEV void conv_tile(const Params& p, int l, int tile, char* smem) {
;     ...
; #pragma unroll 4
;   for (int s = 0; s < 40; ++s) {
;     const int rr = t0 - 15 + s;
;     u32x4 uv = {0u, 0u, 0u, 0u};
;     if (rr >= s_lo && rr < s_hi) uv = *(const u32x4*)(ZU + (size_t)rr * 512 + c0);
;     float u[8];
; #pragma unroll
;     for (int q = 0; q < 4; ++q) { u[2 * q] = lo_bf(uv[q]); u[2 * q + 1] = hi_bf(uv[q]); }
; #pragma unroll
;     for (int q = 7; q > 0; --q) { wk[q][0] = wk[q - 1][0]; wk[q][1] = wk[q - 1][1]; }
;     wk[0][0] = (f32x4){0.f, 0.f, 0.f, 0.f}; wk[0][1] = (f32x4){0.f, 0.f, 0.f, 0.f};
;     if (s <= 30) { wk[0][0] = *(const f32x4*)(wp + s * 512); wk[0][1] = *(const f32x4*)(wp + s * 512 + 4); }
; #pragma unroll
;     for (int t = 0; t < 8; ++t) {
; #pragma unroll
;       for (int j = 0; j < 4; ++j) { acc[t][j] += wk[t][0][j] * u[j]; acc[t][4 + j] += wk[t][1][j] * u[4 + j]; }
;     }
;   }
.Lcv_ok24:
	s_add_i32 s38, s37, 32
	s_max_i32 s38, s38, s36
	s_min_i32 s38, s38, s39
	s_lshl_b32 s38, s38, 10
	s_add_u32 s0, s74, s38
	s_addc_u32 s1, s75, 0
	global_load_dwordx4 v[144:147], v100, s[0:1]
	ds_read_b128 v[128:131], v101 offset:51200
	ds_read_b128 v[132:135], v101 offset:51216
	s_waitcnt lgkmcnt(2)
	v_pk_fma_f32 v[4:5], v[120:121], v[176:177], v[4:5]
	v_pk_fma_f32 v[6:7], v[122:123], v[178:179], v[6:7]
	v_pk_fma_f32 v[12:13], v[124:125], v[180:181], v[12:13]
	v_pk_fma_f32 v[14:15], v[126:127], v[182:183], v[14:15]
	v_pk_fma_f32 v[142:143], v[112:113], v[176:177], v[142:143]
	v_pk_fma_f32 v[138:139], v[114:115], v[178:179], v[138:139]
	v_pk_fma_f32 v[140:141], v[116:117], v[180:181], v[140:141]
	v_pk_fma_f32 v[136:137], v[118:119], v[182:183], v[136:137]
	v_pk_fma_f32 v[110:111], v[48:49], v[176:177], v[110:111]
	v_pk_fma_f32 v[106:107], v[50:51], v[178:179], v[106:107]
	v_pk_fma_f32 v[108:109], v[52:53], v[180:181], v[108:109]
	v_pk_fma_f32 v[104:105], v[54:55], v[182:183], v[104:105]
	v_pk_fma_f32 v[94:95], v[40:41], v[176:177], v[94:95]
	v_pk_fma_f32 v[90:91], v[42:43], v[178:179], v[90:91]
	v_pk_fma_f32 v[92:93], v[44:45], v[180:181], v[92:93]
	v_pk_fma_f32 v[88:89], v[46:47], v[182:183], v[88:89]
	v_pk_fma_f32 v[86:87], v[32:33], v[176:177], v[86:87]
	v_pk_fma_f32 v[82:83], v[34:35], v[178:179], v[82:83]
	v_pk_fma_f32 v[84:85], v[36:37], v[180:181], v[84:85]
	v_pk_fma_f32 v[80:81], v[38:39], v[182:183], v[80:81]
	v_pk_fma_f32 v[78:79], v[24:25], v[176:177], v[78:79]
	v_pk_fma_f32 v[74:75], v[26:27], v[178:179], v[74:75]
	v_pk_fma_f32 v[76:77], v[28:29], v[180:181], v[76:77]
	v_pk_fma_f32 v[72:73], v[30:31], v[182:183], v[72:73]
	v_pk_fma_f32 v[70:71], v[16:17], v[176:177], v[70:71]
	v_pk_fma_f32 v[66:67], v[18:19], v[178:179], v[66:67]
	v_pk_fma_f32 v[68:69], v[20:21], v[180:181], v[68:69]
	v_pk_fma_f32 v[64:65], v[22:23], v[182:183], v[64:65]
	v_pk_fma_f32 v[62:63], v[0:1], v[176:177], v[62:63]
	v_pk_fma_f32 v[58:59], v[2:3], v[178:179], v[58:59]
	v_pk_fma_f32 v[60:61], v[8:9], v[180:181], v[60:61]
	v_pk_fma_f32 v[56:57], v[10:11], v[182:183], v[56:57]
	s_waitcnt vmcnt(7)
	v_lshlrev_b32_e32 v186, 16, v148
	v_and_b32_e32 v187, 0xffff0000, v148
	v_lshlrev_b32_e32 v190, 16, v149
	v_and_b32_e32 v191, 0xffff0000, v149
	v_lshlrev_b32_e32 v192, 16, v150
	v_and_b32_e32 v193, 0xffff0000, v150
	v_lshlrev_b32_e32 v194, 16, v151
	v_and_b32_e32 v195, 0xffff0000, v151
	s_add_i32 s100, s37, 25
	s_cmp_ge_i32 s100, s36
	s_cselect_b32 s101, 1, 0
	s_cmp_lt_i32 s100, s31
	s_cselect_b32 s38, 1, 0
	s_and_b32 s101, s101, s38
	s_cbranch_scc1 .Lcv_ok25
	v_mov_b32_e32 v186, 0
	v_mov_b32_e32 v187, 0
	v_mov_b32_e32 v190, 0
	v_mov_b32_e32 v191, 0
	v_mov_b32_e32 v192, 0
	v_mov_b32_e32 v193, 0
	v_mov_b32_e32 v194, 0
	v_mov_b32_e32 v195, 0
.Lcv_ok25:
	s_add_i32 s38, s37, 33
	s_max_i32 s38, s38, s36
	s_min_i32 s38, s38, s39
	s_lshl_b32 s38, s38, 10
	s_add_u32 s0, s74, s38
	s_addc_u32 s1, s75, 0
	global_load_dwordx4 v[148:151], v100, s[0:1]
	ds_read_b128 v[0:3], v101 offset:53248
	ds_read_b128 v[8:11], v101 offset:53264
	s_waitcnt lgkmcnt(2)
	v_pk_fma_f32 v[4:5], v[128:129], v[186:187], v[4:5]
	v_pk_fma_f32 v[6:7], v[130:131], v[190:191], v[6:7]
	v_pk_fma_f32 v[12:13], v[132:133], v[192:193], v[12:13]
	v_pk_fma_f32 v[14:15], v[134:135], v[194:195], v[14:15]
	v_pk_fma_f32 v[142:143], v[120:121], v[186:187], v[142:143]
	v_pk_fma_f32 v[138:139], v[122:123], v[190:191], v[138:139]
	v_pk_fma_f32 v[140:141], v[124:125], v[192:193], v[140:141]
	v_pk_fma_f32 v[136:137], v[126:127], v[194:195], v[136:137]
	v_pk_fma_f32 v[110:111], v[112:113], v[186:187], v[110:111]
	v_pk_fma_f32 v[106:107], v[114:115], v[190:191], v[106:107]
	v_pk_fma_f32 v[108:109], v[116:117], v[192:193], v[108:109]
	v_pk_fma_f32 v[104:105], v[118:119], v[194:195], v[104:105]
	v_pk_fma_f32 v[94:95], v[48:49], v[186:187], v[94:95]
	v_pk_fma_f32 v[90:91], v[50:51], v[190:191], v[90:91]
	v_pk_fma_f32 v[92:93], v[52:53], v[192:193], v[92:93]
	v_pk_fma_f32 v[88:89], v[54:55], v[194:195], v[88:89]
	v_pk_fma_f32 v[86:87], v[40:41], v[186:187], v[86:87]
	v_pk_fma_f32 v[82:83], v[42:43], v[190:191], v[82:83]
	v_pk_fma_f32 v[84:85], v[44:45], v[192:193], v[84:85]
	v_pk_fma_f32 v[80:81], v[46:47], v[194:195], v[80:81]
	v_pk_fma_f32 v[78:79], v[32:33], v[186:187], v[78:79]
	v_pk_fma_f32 v[74:75], v[34:35], v[190:191], v[74:75]
	v_pk_fma_f32 v[76:77], v[36:37], v[192:193], v[76:77]
	v_pk_fma_f32 v[72:73], v[38:39], v[194:195], v[72:73]
	v_pk_fma_f32 v[70:71], v[24:25], v[186:187], v[70:71]
	v_pk_fma_f32 v[66:67], v[26:27], v[190:191], v[66:67]
	v_pk_fma_f32 v[68:69], v[28:29], v[192:193], v[68:69]
	v_pk_fma_f32 v[64:65], v[30:31], v[194:195], v[64:65]
	v_pk_fma_f32 v[62:63], v[16:17], v[186:187], v[62:63]
	v_pk_fma_f32 v[58:59], v[18:19], v[190:191], v[58:59]
	v_pk_fma_f32 v[60:61], v[20:21], v[192:193], v[60:61]
	v_pk_fma_f32 v[56:57], v[22:23], v[194:195], v[56:57]
	s_waitcnt vmcnt(7)
	v_lshlrev_b32_e32 v176, 16, v152
	v_and_b32_e32 v177, 0xffff0000, v152
	v_lshlrev_b32_e32 v178, 16, v153
	v_and_b32_e32 v179, 0xffff0000, v153
	v_lshlrev_b32_e32 v180, 16, v154
	v_and_b32_e32 v181, 0xffff0000, v154
	v_lshlrev_b32_e32 v182, 16, v155
	v_and_b32_e32 v183, 0xffff0000, v155
	s_add_i32 s100, s37, 26
	s_cmp_ge_i32 s100, s36
	s_cselect_b32 s101, 1, 0
	s_cmp_lt_i32 s100, s31
	s_cselect_b32 s38, 1, 0
	s_and_b32 s101, s101, s38
	s_cbranch_scc1 .Lcv_ok26
	v_mov_b32_e32 v176, 0
	v_mov_b32_e32 v177, 0
	v_mov_b32_e32 v178, 0
	v_mov_b32_e32 v179, 0
	v_mov_b32_e32 v180, 0
	v_mov_b32_e32 v181, 0
	v_mov_b32_e32 v182, 0
	v_mov_b32_e32 v183, 0
; DEV float lo_bf(unsigned u) { return __uint_as_float(u << 16); }
; DEV float hi_bf(unsigned u) { return __uint_as_float(u & 0xffff0000u); }
; DEV void conv_tile(const Params& p, int l, int tile, char* smem) {
;     ...
; #pragma unroll 4
;   for (int s = 0; s < 40; ++s) {
;     const int rr = t0 - 15 + s;
;     u32x4 uv = {0u, 0u, 0u, 0u};
;     if (rr >= s_lo && rr < s_hi) uv = *(const u32x4*)(ZU + (size_t)rr * 512 + c0);
;     float u[8];
; #pragma unroll
;     for (int q = 0; q < 4; ++q) { u[2 * q] = lo_bf(uv[q]); u[2 * q + 1] = hi_bf(uv[q]); }
; #pragma unroll
;     for (int q = 7; q > 0; --q) { wk[q][0] = wk[q - 1][0]; wk[q][1] = wk[q - 1][1]; }
;     wk[0][0] = (f32x4){0.f, 0.f, 0.f, 0.f}; wk[0][1] = (f32x4){0.f, 0.f, 0.f, 0.f};
;     if (s <= 30) { wk[0][0] = *(const f32x4*)(wp + s * 512); wk[0][1] = *(const f32x4*)(wp + s * 512 + 4); }
; #pragma unroll
;     for (int t = 0; t < 8; ++t) {
; #pragma unroll
;       for (int j = 0; j < 4; ++j) { acc[t][j] += wk[t][0][j] * u[j]; acc[t][4 + j] += wk[t][1][j] * u[4 + j]; }
;     }
;   }
.Lcv_ok26:
	s_add_i32 s38, s37, 34
	s_max_i32 s38, s38, s36
	s_min_i32 s38, s38, s39
	s_lshl_b32 s38, s38, 10
	s_add_u32 s0, s74, s38
	s_addc_u32 s1, s75, 0
	global_load_dwordx4 v[152:155], v100, s[0:1]
	ds_read_b128 v[16:19], v101 offset:55296
	ds_read_b128 v[20:23], v101 offset:55312
	s_waitcnt lgkmcnt(2)
	v_pk_fma_f32 v[4:5], v[0:1], v[176:177], v[4:5]
	v_pk_fma_f32 v[6:7], v[2:3], v[178:179], v[6:7]
	v_pk_fma_f32 v[12:13], v[8:9], v[180:181], v[12:13]
	v_pk_fma_f32 v[14:15], v[10:11], v[182:183], v[14:15]
	v_pk_fma_f32 v[142:143], v[128:129], v[176:177], v[142:143]
	v_pk_fma_f32 v[138:139], v[130:131], v[178:179], v[138:139]
	v_pk_fma_f32 v[140:141], v[132:133], v[180:181], v[140:141]
	v_pk_fma_f32 v[136:137], v[134:135], v[182:183], v[136:137]
	v_pk_fma_f32 v[110:111], v[120:121], v[176:177], v[110:111]
	v_pk_fma_f32 v[106:107], v[122:123], v[178:179], v[106:107]
	v_pk_fma_f32 v[108:109], v[124:125], v[180:181], v[108:109]
	v_pk_fma_f32 v[104:105], v[126:127], v[182:183], v[104:105]
	v_pk_fma_f32 v[94:95], v[112:113], v[176:177], v[94:95]
	v_pk_fma_f32 v[90:91], v[114:115], v[178:179], v[90:91]
	v_pk_fma_f32 v[92:93], v[116:117], v[180:181], v[92:93]
	v_pk_fma_f32 v[88:89], v[118:119], v[182:183], v[88:89]
	v_pk_fma_f32 v[86:87], v[48:49], v[176:177], v[86:87]
	v_pk_fma_f32 v[82:83], v[50:51], v[178:179], v[82:83]
	v_pk_fma_f32 v[84:85], v[52:53], v[180:181], v[84:85]
	v_pk_fma_f32 v[80:81], v[54:55], v[182:183], v[80:81]
	v_pk_fma_f32 v[78:79], v[40:41], v[176:177], v[78:79]
	v_pk_fma_f32 v[74:75], v[42:43], v[178:179], v[74:75]
	v_pk_fma_f32 v[76:77], v[44:45], v[180:181], v[76:77]
	v_pk_fma_f32 v[72:73], v[46:47], v[182:183], v[72:73]
	v_pk_fma_f32 v[70:71], v[32:33], v[176:177], v[70:71]
	v_pk_fma_f32 v[66:67], v[34:35], v[178:179], v[66:67]
	v_pk_fma_f32 v[68:69], v[36:37], v[180:181], v[68:69]
	v_pk_fma_f32 v[64:65], v[38:39], v[182:183], v[64:65]
	v_pk_fma_f32 v[62:63], v[24:25], v[176:177], v[62:63]
	v_pk_fma_f32 v[58:59], v[26:27], v[178:179], v[58:59]
	v_pk_fma_f32 v[60:61], v[28:29], v[180:181], v[60:61]
	v_pk_fma_f32 v[56:57], v[30:31], v[182:183], v[56:57]
	s_waitcnt vmcnt(7)
	v_lshlrev_b32_e32 v186, 16, v156
	v_and_b32_e32 v187, 0xffff0000, v156
	v_lshlrev_b32_e32 v190, 16, v157
	v_and_b32_e32 v191, 0xffff0000, v157
	v_lshlrev_b32_e32 v192, 16, v158
	v_and_b32_e32 v193, 0xffff0000, v158
	v_lshlrev_b32_e32 v194, 16, v159
	v_and_b32_e32 v195, 0xffff0000, v159
	s_add_i32 s100, s37, 27
	s_cmp_ge_i32 s100, s36
	s_cselect_b32 s101, 1, 0
	s_cmp_lt_i32 s100, s31
	s_cselect_b32 s38, 1, 0
	s_and_b32 s101, s101, s38
	s_cbranch_scc1 .Lcv_ok27
	v_mov_b32_e32 v186, 0
	v_mov_b32_e32 v187, 0
	v_mov_b32_e32 v190, 0
	v_mov_b32_e32 v191, 0
	v_mov_b32_e32 v192, 0
	v_mov_b32_e32 v193, 0
	v_mov_b32_e32 v194, 0
	v_mov_b32_e32 v195, 0
.Lcv_ok27:
	s_add_i32 s38, s37, 35
	s_max_i32 s38, s38, s36
	s_min_i32 s38, s38, s39
	s_lshl_b32 s38, s38, 10
	s_add_u32 s0, s74, s38
	s_addc_u32 s1, s75, 0
	global_load_dwordx4 v[156:159], v100, s[0:1]
	ds_read_b128 v[24:27], v101 offset:57344
	ds_read_b128 v[28:31], v101 offset:57360
	s_waitcnt lgkmcnt(2)
	v_pk_fma_f32 v[4:5], v[16:17], v[186:187], v[4:5]
	v_pk_fma_f32 v[6:7], v[18:19], v[190:191], v[6:7]
	v_pk_fma_f32 v[12:13], v[20:21], v[192:193], v[12:13]
	v_pk_fma_f32 v[14:15], v[22:23], v[194:195], v[14:15]
	v_pk_fma_f32 v[142:143], v[0:1], v[186:187], v[142:143]
	v_pk_fma_f32 v[138:139], v[2:3], v[190:191], v[138:139]
	v_pk_fma_f32 v[140:141], v[8:9], v[192:193], v[140:141]
	v_pk_fma_f32 v[136:137], v[10:11], v[194:195], v[136:137]
	v_pk_fma_f32 v[110:111], v[128:129], v[186:187], v[110:111]
	v_pk_fma_f32 v[106:107], v[130:131], v[190:191], v[106:107]
	v_pk_fma_f32 v[108:109], v[132:133], v[192:193], v[108:109]
	v_pk_fma_f32 v[104:105], v[134:135], v[194:195], v[104:105]
	v_pk_fma_f32 v[94:95], v[120:121], v[186:187], v[94:95]
	v_pk_fma_f32 v[90:91], v[122:123], v[190:191], v[90:91]
	v_pk_fma_f32 v[92:93], v[124:125], v[192:193], v[92:93]
	v_pk_fma_f32 v[88:89], v[126:127], v[194:195], v[88:89]
	v_pk_fma_f32 v[86:87], v[112:113], v[186:187], v[86:87]
	v_pk_fma_f32 v[82:83], v[114:115], v[190:191], v[82:83]
	v_pk_fma_f32 v[84:85], v[116:117], v[192:193], v[84:85]
	v_pk_fma_f32 v[80:81], v[118:119], v[194:195], v[80:81]
	v_pk_fma_f32 v[78:79], v[48:49], v[186:187], v[78:79]
	v_pk_fma_f32 v[74:75], v[50:51], v[190:191], v[74:75]
	v_pk_fma_f32 v[76:77], v[52:53], v[192:193], v[76:77]
	v_pk_fma_f32 v[72:73], v[54:55], v[194:195], v[72:73]
	v_pk_fma_f32 v[70:71], v[40:41], v[186:187], v[70:71]
	v_pk_fma_f32 v[66:67], v[42:43], v[190:191], v[66:67]
	v_pk_fma_f32 v[68:69], v[44:45], v[192:193], v[68:69]
	v_pk_fma_f32 v[64:65], v[46:47], v[194:195], v[64:65]
	v_pk_fma_f32 v[62:63], v[32:33], v[186:187], v[62:63]
	v_pk_fma_f32 v[58:59], v[34:35], v[190:191], v[58:59]
	v_pk_fma_f32 v[60:61], v[36:37], v[192:193], v[60:61]
	v_pk_fma_f32 v[56:57], v[38:39], v[194:195], v[56:57]
	s_waitcnt vmcnt(7)
	v_lshlrev_b32_e32 v176, 16, v160
	v_and_b32_e32 v177, 0xffff0000, v160
	v_lshlrev_b32_e32 v178, 16, v161
	v_and_b32_e32 v179, 0xffff0000, v161
	v_lshlrev_b32_e32 v180, 16, v162
	v_and_b32_e32 v181, 0xffff0000, v162
	v_lshlrev_b32_e32 v182, 16, v163
	v_and_b32_e32 v183, 0xffff0000, v163
	s_add_i32 s100, s37, 28
	s_cmp_ge_i32 s100, s36
	s_cselect_b32 s101, 1, 0
	s_cmp_lt_i32 s100, s31
	s_cselect_b32 s38, 1, 0
	s_and_b32 s101, s101, s38
	s_cbranch_scc1 .Lcv_ok28
	v_mov_b32_e32 v176, 0
	v_mov_b32_e32 v177, 0
	v_mov_b32_e32 v178, 0
	v_mov_b32_e32 v179, 0
	v_mov_b32_e32 v180, 0
	v_mov_b32_e32 v181, 0
	v_mov_b32_e32 v182, 0
	v_mov_b32_e32 v183, 0
; DEV float lo_bf(unsigned u) { return __uint_as_float(u << 16); }
; DEV float hi_bf(unsigned u) { return __uint_as_float(u & 0xffff0000u); }
; DEV void conv_tile(const Params& p, int l, int tile, char* smem) {
;     ...
; #pragma unroll 4
;   for (int s = 0; s < 40; ++s) {
;     const int rr = t0 - 15 + s;
;     u32x4 uv = {0u, 0u, 0u, 0u};
;     if (rr >= s_lo && rr < s_hi) uv = *(const u32x4*)(ZU + (size_t)rr * 512 + c0);
;     float u[8];
; #pragma unroll
;     for (int q = 0; q < 4; ++q) { u[2 * q] = lo_bf(uv[q]); u[2 * q + 1] = hi_bf(uv[q]); }
; #pragma unroll
;     for (int q = 7; q > 0; --q) { wk[q][0] = wk[q - 1][0]; wk[q][1] = wk[q - 1][1]; }
;     wk[0][0] = (f32x4){0.f, 0.f, 0.f, 0.f}; wk[0][1] = (f32x4){0.f, 0.f, 0.f, 0.f};
;     if (s <= 30) { wk[0][0] = *(const f32x4*)(wp + s * 512); wk[0][1] = *(const f32x4*)(wp + s * 512 + 4); }
; #pragma unroll
;     for (int t = 0; t < 8; ++t) {
; #pragma unroll
;       for (int j = 0; j < 4; ++j) { acc[t][j] += wk[t][0][j] * u[j]; acc[t][4 + j] += wk[t][1][j] * u[4 + j]; }
;     }
;   }
.Lcv_ok28:
	s_add_i32 s38, s37, 36
	s_max_i32 s38, s38, s36
	s_min_i32 s38, s38, s39
	s_lshl_b32 s38, s38, 10
	s_add_u32 s0, s74, s38
	s_addc_u32 s1, s75, 0
	global_load_dwordx4 v[160:163], v100, s[0:1]
	ds_read_b128 v[32:35], v101 offset:59392
	ds_read_b128 v[36:39], v101 offset:59408
	s_waitcnt lgkmcnt(2)
	v_pk_fma_f32 v[4:5], v[24:25], v[176:177], v[4:5]
	v_pk_fma_f32 v[6:7], v[26:27], v[178:179], v[6:7]
	v_pk_fma_f32 v[12:13], v[28:29], v[180:181], v[12:13]
	v_pk_fma_f32 v[14:15], v[30:31], v[182:183], v[14:15]
	v_pk_fma_f32 v[142:143], v[16:17], v[176:177], v[142:143]
	v_pk_fma_f32 v[138:139], v[18:19], v[178:179], v[138:139]
	v_pk_fma_f32 v[140:141], v[20:21], v[180:181], v[140:141]
	v_pk_fma_f32 v[136:137], v[22:23], v[182:183], v[136:137]
	v_pk_fma_f32 v[110:111], v[0:1], v[176:177], v[110:111]
	v_pk_fma_f32 v[106:107], v[2:3], v[178:179], v[106:107]
	v_pk_fma_f32 v[108:109], v[8:9], v[180:181], v[108:109]
	v_pk_fma_f32 v[104:105], v[10:11], v[182:183], v[104:105]
	v_pk_fma_f32 v[94:95], v[128:129], v[176:177], v[94:95]
	v_pk_fma_f32 v[90:91], v[130:131], v[178:179], v[90:91]
	v_pk_fma_f32 v[92:93], v[132:133], v[180:181], v[92:93]
	v_pk_fma_f32 v[88:89], v[134:135], v[182:183], v[88:89]
	v_pk_fma_f32 v[86:87], v[120:121], v[176:177], v[86:87]
	v_pk_fma_f32 v[82:83], v[122:123], v[178:179], v[82:83]
	v_pk_fma_f32 v[84:85], v[124:125], v[180:181], v[84:85]
	v_pk_fma_f32 v[80:81], v[126:127], v[182:183], v[80:81]
	v_pk_fma_f32 v[78:79], v[112:113], v[176:177], v[78:79]
	v_pk_fma_f32 v[74:75], v[114:115], v[178:179], v[74:75]
	v_pk_fma_f32 v[76:77], v[116:117], v[180:181], v[76:77]
	v_pk_fma_f32 v[72:73], v[118:119], v[182:183], v[72:73]
	v_pk_fma_f32 v[70:71], v[48:49], v[176:177], v[70:71]
	v_pk_fma_f32 v[66:67], v[50:51], v[178:179], v[66:67]
	v_pk_fma_f32 v[68:69], v[52:53], v[180:181], v[68:69]
	v_pk_fma_f32 v[64:65], v[54:55], v[182:183], v[64:65]
	v_pk_fma_f32 v[62:63], v[40:41], v[176:177], v[62:63]
	v_pk_fma_f32 v[58:59], v[42:43], v[178:179], v[58:59]
	v_pk_fma_f32 v[60:61], v[44:45], v[180:181], v[60:61]
	v_pk_fma_f32 v[56:57], v[46:47], v[182:183], v[56:57]
	s_waitcnt vmcnt(7)
	v_lshlrev_b32_e32 v186, 16, v164
	v_and_b32_e32 v187, 0xffff0000, v164
	v_lshlrev_b32_e32 v190, 16, v165
	v_and_b32_e32 v191, 0xffff0000, v165
	v_lshlrev_b32_e32 v192, 16, v166
	v_and_b32_e32 v193, 0xffff0000, v166
	v_lshlrev_b32_e32 v194, 16, v167
	v_and_b32_e32 v195, 0xffff0000, v167
	s_add_i32 s100, s37, 29
	s_cmp_ge_i32 s100, s36
	s_cselect_b32 s101, 1, 0
	s_cmp_lt_i32 s100, s31
	s_cselect_b32 s38, 1, 0
	s_and_b32 s101, s101, s38
	s_cbranch_scc1 .Lcv_ok29
	v_mov_b32_e32 v186, 0
	v_mov_b32_e32 v187, 0
	v_mov_b32_e32 v190, 0
	v_mov_b32_e32 v191, 0
	v_mov_b32_e32 v192, 0
	v_mov_b32_e32 v193, 0
	v_mov_b32_e32 v194, 0
	v_mov_b32_e32 v195, 0
.Lcv_ok29:
	s_add_i32 s38, s37, 37
	s_max_i32 s38, s38, s36
	s_min_i32 s38, s38, s39
	s_lshl_b32 s38, s38, 10
	s_add_u32 s0, s74, s38
	s_addc_u32 s1, s75, 0
	global_load_dwordx4 v[164:167], v100, s[0:1]
	ds_read_b128 v[40:43], v101 offset:61440
	ds_read_b128 v[44:47], v101 offset:61456
	s_waitcnt lgkmcnt(2)
	v_pk_fma_f32 v[4:5], v[32:33], v[186:187], v[4:5]
	v_pk_fma_f32 v[6:7], v[34:35], v[190:191], v[6:7]
	v_pk_fma_f32 v[12:13], v[36:37], v[192:193], v[12:13]
	v_pk_fma_f32 v[14:15], v[38:39], v[194:195], v[14:15]
	v_pk_fma_f32 v[142:143], v[24:25], v[186:187], v[142:143]
	v_pk_fma_f32 v[138:139], v[26:27], v[190:191], v[138:139]
	v_pk_fma_f32 v[140:141], v[28:29], v[192:193], v[140:141]
	v_pk_fma_f32 v[136:137], v[30:31], v[194:195], v[136:137]
	v_pk_fma_f32 v[110:111], v[16:17], v[186:187], v[110:111]
	v_pk_fma_f32 v[106:107], v[18:19], v[190:191], v[106:107]
	v_pk_fma_f32 v[108:109], v[20:21], v[192:193], v[108:109]
	v_pk_fma_f32 v[104:105], v[22:23], v[194:195], v[104:105]
	v_pk_fma_f32 v[94:95], v[0:1], v[186:187], v[94:95]
	v_pk_fma_f32 v[90:91], v[2:3], v[190:191], v[90:91]
	v_pk_fma_f32 v[92:93], v[8:9], v[192:193], v[92:93]
	v_pk_fma_f32 v[88:89], v[10:11], v[194:195], v[88:89]
	v_pk_fma_f32 v[86:87], v[128:129], v[186:187], v[86:87]
	v_pk_fma_f32 v[82:83], v[130:131], v[190:191], v[82:83]
	v_pk_fma_f32 v[84:85], v[132:133], v[192:193], v[84:85]
	v_pk_fma_f32 v[80:81], v[134:135], v[194:195], v[80:81]
	v_pk_fma_f32 v[78:79], v[120:121], v[186:187], v[78:79]
	v_pk_fma_f32 v[74:75], v[122:123], v[190:191], v[74:75]
	v_pk_fma_f32 v[76:77], v[124:125], v[192:193], v[76:77]
	v_pk_fma_f32 v[72:73], v[126:127], v[194:195], v[72:73]
	v_pk_fma_f32 v[70:71], v[112:113], v[186:187], v[70:71]
	v_pk_fma_f32 v[66:67], v[114:115], v[190:191], v[66:67]
	v_pk_fma_f32 v[68:69], v[116:117], v[192:193], v[68:69]
	v_pk_fma_f32 v[64:65], v[118:119], v[194:195], v[64:65]
	v_pk_fma_f32 v[62:63], v[48:49], v[186:187], v[62:63]
	v_pk_fma_f32 v[58:59], v[50:51], v[190:191], v[58:59]
	v_pk_fma_f32 v[60:61], v[52:53], v[192:193], v[60:61]
	v_pk_fma_f32 v[56:57], v[54:55], v[194:195], v[56:57]
	s_waitcnt vmcnt(7)
	v_lshlrev_b32_e32 v176, 16, v168
	v_and_b32_e32 v177, 0xffff0000, v168
	v_lshlrev_b32_e32 v178, 16, v169
	v_and_b32_e32 v179, 0xffff0000, v169
	v_lshlrev_b32_e32 v180, 16, v170
	v_and_b32_e32 v181, 0xffff0000, v170
	v_lshlrev_b32_e32 v182, 16, v171
	v_and_b32_e32 v183, 0xffff0000, v171
	s_add_i32 s100, s37, 30
	s_cmp_ge_i32 s100, s36
	s_cselect_b32 s101, 1, 0
	s_cmp_lt_i32 s100, s31
	s_cselect_b32 s38, 1, 0
	s_and_b32 s101, s101, s38
	s_cbranch_scc1 .Lcv_ok30
	v_mov_b32_e32 v176, 0
	v_mov_b32_e32 v177, 0
	v_mov_b32_e32 v178, 0
	v_mov_b32_e32 v179, 0
	v_mov_b32_e32 v180, 0
	v_mov_b32_e32 v181, 0
	v_mov_b32_e32 v182, 0
	v_mov_b32_e32 v183, 0
; DEV float lo_bf(unsigned u) { return __uint_as_float(u << 16); }
; DEV float hi_bf(unsigned u) { return __uint_as_float(u & 0xffff0000u); }
; DEV void conv_tile(const Params& p, int l, int tile, char* smem) {
;     ...
; #pragma unroll 4
;   for (int s = 0; s < 40; ++s) {
;     const int rr = t0 - 15 + s;
;     u32x4 uv = {0u, 0u, 0u, 0u};
;     if (rr >= s_lo && rr < s_hi) uv = *(const u32x4*)(ZU + (size_t)rr * 512 + c0);
;     float u[8];
; #pragma unroll
;     for (int q = 0; q < 4; ++q) { u[2 * q] = lo_bf(uv[q]); u[2 * q + 1] = hi_bf(uv[q]); }
; #pragma unroll
;     for (int q = 7; q > 0; --q) { wk[q][0] = wk[q - 1][0]; wk[q][1] = wk[q - 1][1]; }
;     wk[0][0] = (f32x4){0.f, 0.f, 0.f, 0.f}; wk[0][1] = (f32x4){0.f, 0.f, 0.f, 0.f};
;     if (s <= 30) { wk[0][0] = *(const f32x4*)(wp + s * 512); wk[0][1] = *(const f32x4*)(wp + s * 512 + 4); }
; #pragma unroll
;     for (int t = 0; t < 8; ++t) {
; #pragma unroll
;       for (int j = 0; j < 4; ++j) { acc[t][j] += wk[t][0][j] * u[j]; acc[t][4 + j] += wk[t][1][j] * u[4 + j]; }
;     }
;   }
.Lcv_ok30:
	s_waitcnt lgkmcnt(0)
	v_pk_fma_f32 v[4:5], v[40:41], v[176:177], v[4:5]
	v_pk_fma_f32 v[6:7], v[42:43], v[178:179], v[6:7]
	v_pk_fma_f32 v[12:13], v[44:45], v[180:181], v[12:13]
	v_pk_fma_f32 v[14:15], v[46:47], v[182:183], v[14:15]
	v_pk_fma_f32 v[142:143], v[32:33], v[176:177], v[142:143]
	v_pk_fma_f32 v[138:139], v[34:35], v[178:179], v[138:139]
	v_pk_fma_f32 v[140:141], v[36:37], v[180:181], v[140:141]
	v_pk_fma_f32 v[136:137], v[38:39], v[182:183], v[136:137]
	v_pk_fma_f32 v[110:111], v[24:25], v[176:177], v[110:111]
	v_pk_fma_f32 v[106:107], v[26:27], v[178:179], v[106:107]
	v_pk_fma_f32 v[108:109], v[28:29], v[180:181], v[108:109]
	v_pk_fma_f32 v[104:105], v[30:31], v[182:183], v[104:105]
	v_pk_fma_f32 v[94:95], v[16:17], v[176:177], v[94:95]
	v_pk_fma_f32 v[90:91], v[18:19], v[178:179], v[90:91]
	v_pk_fma_f32 v[92:93], v[20:21], v[180:181], v[92:93]
	v_pk_fma_f32 v[88:89], v[22:23], v[182:183], v[88:89]
	v_pk_fma_f32 v[86:87], v[0:1], v[176:177], v[86:87]
	v_pk_fma_f32 v[82:83], v[2:3], v[178:179], v[82:83]
	v_pk_fma_f32 v[84:85], v[8:9], v[180:181], v[84:85]
	v_pk_fma_f32 v[80:81], v[10:11], v[182:183], v[80:81]
	v_pk_fma_f32 v[78:79], v[128:129], v[176:177], v[78:79]
	v_pk_fma_f32 v[74:75], v[130:131], v[178:179], v[74:75]
	v_pk_fma_f32 v[76:77], v[132:133], v[180:181], v[76:77]
	v_pk_fma_f32 v[72:73], v[134:135], v[182:183], v[72:73]
	v_pk_fma_f32 v[70:71], v[120:121], v[176:177], v[70:71]
	v_pk_fma_f32 v[66:67], v[122:123], v[178:179], v[66:67]
	v_pk_fma_f32 v[68:69], v[124:125], v[180:181], v[68:69]
	v_pk_fma_f32 v[64:65], v[126:127], v[182:183], v[64:65]
	v_pk_fma_f32 v[62:63], v[112:113], v[176:177], v[62:63]
	v_pk_fma_f32 v[58:59], v[114:115], v[178:179], v[58:59]
	v_pk_fma_f32 v[60:61], v[116:117], v[180:181], v[60:61]
	v_pk_fma_f32 v[56:57], v[118:119], v[182:183], v[56:57]
	s_waitcnt vmcnt(6)
	v_lshlrev_b32_e32 v186, 16, v172
	v_and_b32_e32 v187, 0xffff0000, v172
	v_lshlrev_b32_e32 v190, 16, v173
	v_and_b32_e32 v191, 0xffff0000, v173
	v_lshlrev_b32_e32 v192, 16, v174
	v_and_b32_e32 v193, 0xffff0000, v174
	v_lshlrev_b32_e32 v194, 16, v175
	v_and_b32_e32 v195, 0xffff0000, v175
	s_add_i32 s100, s37, 31
	s_cmp_ge_i32 s100, s36
	s_cselect_b32 s101, 1, 0
	s_cmp_lt_i32 s100, s31
	s_cselect_b32 s38, 1, 0
	s_and_b32 s101, s101, s38
	s_cbranch_scc1 .Lcv_ok31
	v_mov_b32_e32 v186, 0
	v_mov_b32_e32 v187, 0
	v_mov_b32_e32 v190, 0
	v_mov_b32_e32 v191, 0
	v_mov_b32_e32 v192, 0
	v_mov_b32_e32 v193, 0
	v_mov_b32_e32 v194, 0
	v_mov_b32_e32 v195, 0
.Lcv_ok31:
	v_pk_fma_f32 v[142:143], v[40:41], v[186:187], v[142:143]
	v_pk_fma_f32 v[138:139], v[42:43], v[190:191], v[138:139]
	v_pk_fma_f32 v[140:141], v[44:45], v[192:193], v[140:141]
	v_pk_fma_f32 v[136:137], v[46:47], v[194:195], v[136:137]
	v_pk_fma_f32 v[110:111], v[32:33], v[186:187], v[110:111]
	v_pk_fma_f32 v[106:107], v[34:35], v[190:191], v[106:107]
	v_pk_fma_f32 v[108:109], v[36:37], v[192:193], v[108:109]
	v_pk_fma_f32 v[104:105], v[38:39], v[194:195], v[104:105]
	v_pk_fma_f32 v[94:95], v[24:25], v[186:187], v[94:95]
	v_pk_fma_f32 v[90:91], v[26:27], v[190:191], v[90:91]
	v_pk_fma_f32 v[92:93], v[28:29], v[192:193], v[92:93]
	v_pk_fma_f32 v[88:89], v[30:31], v[194:195], v[88:89]
	v_pk_fma_f32 v[86:87], v[16:17], v[186:187], v[86:87]
	v_pk_fma_f32 v[82:83], v[18:19], v[190:191], v[82:83]
	v_pk_fma_f32 v[84:85], v[20:21], v[192:193], v[84:85]
	v_pk_fma_f32 v[80:81], v[22:23], v[194:195], v[80:81]
	v_pk_fma_f32 v[78:79], v[0:1], v[186:187], v[78:79]
	v_pk_fma_f32 v[74:75], v[2:3], v[190:191], v[74:75]
	v_pk_fma_f32 v[76:77], v[8:9], v[192:193], v[76:77]
	v_pk_fma_f32 v[72:73], v[10:11], v[194:195], v[72:73]
	v_pk_fma_f32 v[70:71], v[128:129], v[186:187], v[70:71]
	v_pk_fma_f32 v[66:67], v[130:131], v[190:191], v[66:67]
	v_pk_fma_f32 v[68:69], v[132:133], v[192:193], v[68:69]
	v_pk_fma_f32 v[64:65], v[134:135], v[194:195], v[64:65]
	v_pk_fma_f32 v[62:63], v[120:121], v[186:187], v[62:63]
	v_pk_fma_f32 v[58:59], v[122:123], v[190:191], v[58:59]
	v_pk_fma_f32 v[60:61], v[124:125], v[192:193], v[60:61]
	v_pk_fma_f32 v[56:57], v[126:127], v[194:195], v[56:57]
	s_waitcnt vmcnt(5)
	v_lshlrev_b32_e32 v176, 16, v144
	v_and_b32_e32 v177, 0xffff0000, v144
	v_lshlrev_b32_e32 v178, 16, v145
	v_and_b32_e32 v179, 0xffff0000, v145
	v_lshlrev_b32_e32 v180, 16, v146
	v_and_b32_e32 v181, 0xffff0000, v146
	v_lshlrev_b32_e32 v182, 16, v147
	v_and_b32_e32 v183, 0xffff0000, v147
	s_add_i32 s100, s37, 32
	s_cmp_ge_i32 s100, s36
	s_cselect_b32 s101, 1, 0
	s_cmp_lt_i32 s100, s31
	s_cselect_b32 s38, 1, 0
	s_and_b32 s101, s101, s38
	s_cbranch_scc1 .Lcv_ok32
	v_mov_b32_e32 v176, 0
	v_mov_b32_e32 v177, 0
	v_mov_b32_e32 v178, 0
	v_mov_b32_e32 v179, 0
	v_mov_b32_e32 v180, 0
	v_mov_b32_e32 v181, 0
	v_mov_b32_e32 v182, 0
	v_mov_b32_e32 v183, 0
; DEV float lo_bf(unsigned u) { return __uint_as_float(u << 16); }
; DEV float hi_bf(unsigned u) { return __uint_as_float(u & 0xffff0000u); }
; DEV void conv_tile(const Params& p, int l, int tile, char* smem) {
;     ...
; #pragma unroll 4
;   for (int s = 0; s < 40; ++s) {
;     const int rr = t0 - 15 + s;
;     u32x4 uv = {0u, 0u, 0u, 0u};
;     if (rr >= s_lo && rr < s_hi) uv = *(const u32x4*)(ZU + (size_t)rr * 512 + c0);
;     float u[8];
; #pragma unroll
;     for (int q = 0; q < 4; ++q) { u[2 * q] = lo_bf(uv[q]); u[2 * q + 1] = hi_bf(uv[q]); }
; #pragma unroll
;     for (int q = 7; q > 0; --q) { wk[q][0] = wk[q - 1][0]; wk[q][1] = wk[q - 1][1]; }
;     wk[0][0] = (f32x4){0.f, 0.f, 0.f, 0.f}; wk[0][1] = (f32x4){0.f, 0.f, 0.f, 0.f};
;     if (s <= 30) { wk[0][0] = *(const f32x4*)(wp + s * 512); wk[0][1] = *(const f32x4*)(wp + s * 512 + 4); }
; #pragma unroll
;     for (int t = 0; t < 8; ++t) {
; #pragma unroll
;       for (int j = 0; j < 4; ++j) { acc[t][j] += wk[t][0][j] * u[j]; acc[t][4 + j] += wk[t][1][j] * u[4 + j]; }
;     }
;   }
.Lcv_ok32:
	v_pk_fma_f32 v[110:111], v[40:41], v[176:177], v[110:111]
	v_pk_fma_f32 v[106:107], v[42:43], v[178:179], v[106:107]
	v_pk_fma_f32 v[108:109], v[44:45], v[180:181], v[108:109]
	v_pk_fma_f32 v[104:105], v[46:47], v[182:183], v[104:105]
	v_pk_fma_f32 v[94:95], v[32:33], v[176:177], v[94:95]
	v_pk_fma_f32 v[90:91], v[34:35], v[178:179], v[90:91]
	v_pk_fma_f32 v[92:93], v[36:37], v[180:181], v[92:93]
	v_pk_fma_f32 v[88:89], v[38:39], v[182:183], v[88:89]
	v_pk_fma_f32 v[86:87], v[24:25], v[176:177], v[86:87]
	v_pk_fma_f32 v[82:83], v[26:27], v[178:179], v[82:83]
	v_pk_fma_f32 v[84:85], v[28:29], v[180:181], v[84:85]
	v_pk_fma_f32 v[80:81], v[30:31], v[182:183], v[80:81]
	v_pk_fma_f32 v[78:79], v[16:17], v[176:177], v[78:79]
	v_pk_fma_f32 v[74:75], v[18:19], v[178:179], v[74:75]
	v_pk_fma_f32 v[76:77], v[20:21], v[180:181], v[76:77]
	v_pk_fma_f32 v[72:73], v[22:23], v[182:183], v[72:73]
	v_pk_fma_f32 v[70:71], v[0:1], v[176:177], v[70:71]
	v_pk_fma_f32 v[66:67], v[2:3], v[178:179], v[66:67]
	v_pk_fma_f32 v[68:69], v[8:9], v[180:181], v[68:69]
	v_pk_fma_f32 v[64:65], v[10:11], v[182:183], v[64:65]
	v_pk_fma_f32 v[62:63], v[128:129], v[176:177], v[62:63]
	v_pk_fma_f32 v[58:59], v[130:131], v[178:179], v[58:59]
	v_pk_fma_f32 v[60:61], v[132:133], v[180:181], v[60:61]
	v_pk_fma_f32 v[56:57], v[134:135], v[182:183], v[56:57]
	s_waitcnt vmcnt(4)
	v_lshlrev_b32_e32 v186, 16, v148
	v_and_b32_e32 v187, 0xffff0000, v148
	v_lshlrev_b32_e32 v190, 16, v149
	v_and_b32_e32 v191, 0xffff0000, v149
	v_lshlrev_b32_e32 v192, 16, v150
	v_and_b32_e32 v193, 0xffff0000, v150
	v_lshlrev_b32_e32 v194, 16, v151
	v_and_b32_e32 v195, 0xffff0000, v151
	s_add_i32 s100, s37, 33
	s_cmp_ge_i32 s100, s36
	s_cselect_b32 s101, 1, 0
	s_cmp_lt_i32 s100, s31
	s_cselect_b32 s38, 1, 0
	s_and_b32 s101, s101, s38
	s_cbranch_scc1 .Lcv_ok33
	v_mov_b32_e32 v186, 0
	v_mov_b32_e32 v187, 0
	v_mov_b32_e32 v190, 0
	v_mov_b32_e32 v191, 0
	v_mov_b32_e32 v192, 0
	v_mov_b32_e32 v193, 0
	v_mov_b32_e32 v194, 0
	v_mov_b32_e32 v195, 0
.Lcv_ok33:
	v_pk_fma_f32 v[94:95], v[40:41], v[186:187], v[94:95]
	v_pk_fma_f32 v[90:91], v[42:43], v[190:191], v[90:91]
	v_pk_fma_f32 v[92:93], v[44:45], v[192:193], v[92:93]
	v_pk_fma_f32 v[88:89], v[46:47], v[194:195], v[88:89]
	v_pk_fma_f32 v[86:87], v[32:33], v[186:187], v[86:87]
	v_pk_fma_f32 v[82:83], v[34:35], v[190:191], v[82:83]
	v_pk_fma_f32 v[84:85], v[36:37], v[192:193], v[84:85]
	v_pk_fma_f32 v[80:81], v[38:39], v[194:195], v[80:81]
	v_pk_fma_f32 v[78:79], v[24:25], v[186:187], v[78:79]
	v_pk_fma_f32 v[74:75], v[26:27], v[190:191], v[74:75]
	v_pk_fma_f32 v[76:77], v[28:29], v[192:193], v[76:77]
	v_pk_fma_f32 v[72:73], v[30:31], v[194:195], v[72:73]
	v_pk_fma_f32 v[70:71], v[16:17], v[186:187], v[70:71]
	v_pk_fma_f32 v[66:67], v[18:19], v[190:191], v[66:67]
	v_pk_fma_f32 v[68:69], v[20:21], v[192:193], v[68:69]
	v_pk_fma_f32 v[64:65], v[22:23], v[194:195], v[64:65]
	v_pk_fma_f32 v[62:63], v[0:1], v[186:187], v[62:63]
	v_pk_fma_f32 v[58:59], v[2:3], v[190:191], v[58:59]
	v_pk_fma_f32 v[60:61], v[8:9], v[192:193], v[60:61]
	v_pk_fma_f32 v[56:57], v[10:11], v[194:195], v[56:57]
	s_waitcnt vmcnt(3)
	v_lshlrev_b32_e32 v176, 16, v152
	v_and_b32_e32 v177, 0xffff0000, v152
	v_lshlrev_b32_e32 v178, 16, v153
	v_and_b32_e32 v179, 0xffff0000, v153
	v_lshlrev_b32_e32 v180, 16, v154
	v_and_b32_e32 v181, 0xffff0000, v154
	v_lshlrev_b32_e32 v182, 16, v155
	v_and_b32_e32 v183, 0xffff0000, v155
	s_add_i32 s100, s37, 34
	s_cmp_ge_i32 s100, s36
	s_cselect_b32 s101, 1, 0
	s_cmp_lt_i32 s100, s31
	s_cselect_b32 s38, 1, 0
	s_and_b32 s101, s101, s38
	s_cbranch_scc1 .Lcv_ok34
	v_mov_b32_e32 v176, 0
	v_mov_b32_e32 v177, 0
	v_mov_b32_e32 v178, 0
	v_mov_b32_e32 v179, 0
	v_mov_b32_e32 v180, 0
	v_mov_b32_e32 v181, 0
	v_mov_b32_e32 v182, 0
	v_mov_b32_e32 v183, 0
; DEV float lo_bf(unsigned u) { return __uint_as_float(u << 16); }
; DEV float hi_bf(unsigned u) { return __uint_as_float(u & 0xffff0000u); }
; DEV void conv_tile(const Params& p, int l, int tile, char* smem) {
;     ...
; #pragma unroll 4
;   for (int s = 0; s < 40; ++s) {
;     const int rr = t0 - 15 + s;
;     u32x4 uv = {0u, 0u, 0u, 0u};
;     if (rr >= s_lo && rr < s_hi) uv = *(const u32x4*)(ZU + (size_t)rr * 512 + c0);
;     float u[8];
; #pragma unroll
;     for (int q = 0; q < 4; ++q) { u[2 * q] = lo_bf(uv[q]); u[2 * q + 1] = hi_bf(uv[q]); }
; #pragma unroll
;     for (int q = 7; q > 0; --q) { wk[q][0] = wk[q - 1][0]; wk[q][1] = wk[q - 1][1]; }
;     wk[0][0] = (f32x4){0.f, 0.f, 0.f, 0.f}; wk[0][1] = (f32x4){0.f, 0.f, 0.f, 0.f};
;     if (s <= 30) { wk[0][0] = *(const f32x4*)(wp + s * 512); wk[0][1] = *(const f32x4*)(wp + s * 512 + 4); }
; #pragma unroll
;     for (int t = 0; t < 8; ++t) {
; #pragma unroll
;       for (int j = 0; j < 4; ++j) { acc[t][j] += wk[t][0][j] * u[j]; acc[t][4 + j] += wk[t][1][j] * u[4 + j]; }
;     }
;   }
.Lcv_ok34:
	v_pk_fma_f32 v[86:87], v[40:41], v[176:177], v[86:87]
	v_pk_fma_f32 v[82:83], v[42:43], v[178:179], v[82:83]
	v_pk_fma_f32 v[84:85], v[44:45], v[180:181], v[84:85]
	v_pk_fma_f32 v[80:81], v[46:47], v[182:183], v[80:81]
	v_pk_fma_f32 v[78:79], v[32:33], v[176:177], v[78:79]
	v_pk_fma_f32 v[74:75], v[34:35], v[178:179], v[74:75]
	v_pk_fma_f32 v[76:77], v[36:37], v[180:181], v[76:77]
	v_pk_fma_f32 v[72:73], v[38:39], v[182:183], v[72:73]
	v_pk_fma_f32 v[70:71], v[24:25], v[176:177], v[70:71]
	v_pk_fma_f32 v[66:67], v[26:27], v[178:179], v[66:67]
	v_pk_fma_f32 v[68:69], v[28:29], v[180:181], v[68:69]
	v_pk_fma_f32 v[64:65], v[30:31], v[182:183], v[64:65]
	v_pk_fma_f32 v[62:63], v[16:17], v[176:177], v[62:63]
	v_pk_fma_f32 v[58:59], v[18:19], v[178:179], v[58:59]
	v_pk_fma_f32 v[60:61], v[20:21], v[180:181], v[60:61]
	v_pk_fma_f32 v[56:57], v[22:23], v[182:183], v[56:57]
	s_waitcnt vmcnt(2)
	v_lshlrev_b32_e32 v186, 16, v156
	v_and_b32_e32 v187, 0xffff0000, v156
	v_lshlrev_b32_e32 v190, 16, v157
	v_and_b32_e32 v191, 0xffff0000, v157
	v_lshlrev_b32_e32 v192, 16, v158
	v_and_b32_e32 v193, 0xffff0000, v158
	v_lshlrev_b32_e32 v194, 16, v159
	v_and_b32_e32 v195, 0xffff0000, v159
	s_add_i32 s100, s37, 35
	s_cmp_ge_i32 s100, s36
	s_cselect_b32 s101, 1, 0
	s_cmp_lt_i32 s100, s31
	s_cselect_b32 s38, 1, 0
	s_and_b32 s101, s101, s38
	s_cbranch_scc1 .Lcv_ok35
	v_mov_b32_e32 v186, 0
	v_mov_b32_e32 v187, 0
	v_mov_b32_e32 v190, 0
	v_mov_b32_e32 v191, 0
	v_mov_b32_e32 v192, 0
	v_mov_b32_e32 v193, 0
	v_mov_b32_e32 v194, 0
	v_mov_b32_e32 v195, 0
.Lcv_ok35:
	v_pk_fma_f32 v[78:79], v[40:41], v[186:187], v[78:79]
	v_pk_fma_f32 v[74:75], v[42:43], v[190:191], v[74:75]
	v_pk_fma_f32 v[76:77], v[44:45], v[192:193], v[76:77]
	v_pk_fma_f32 v[72:73], v[46:47], v[194:195], v[72:73]
	v_pk_fma_f32 v[70:71], v[32:33], v[186:187], v[70:71]
	v_pk_fma_f32 v[66:67], v[34:35], v[190:191], v[66:67]
	v_pk_fma_f32 v[68:69], v[36:37], v[192:193], v[68:69]
	v_pk_fma_f32 v[64:65], v[38:39], v[194:195], v[64:65]
	v_pk_fma_f32 v[62:63], v[24:25], v[186:187], v[62:63]
	v_pk_fma_f32 v[58:59], v[26:27], v[190:191], v[58:59]
	v_pk_fma_f32 v[60:61], v[28:29], v[192:193], v[60:61]
	v_pk_fma_f32 v[56:57], v[30:31], v[194:195], v[56:57]
	s_waitcnt vmcnt(1)
	v_lshlrev_b32_e32 v176, 16, v160
	v_and_b32_e32 v177, 0xffff0000, v160
	v_lshlrev_b32_e32 v178, 16, v161
	v_and_b32_e32 v179, 0xffff0000, v161
	v_lshlrev_b32_e32 v180, 16, v162
	v_and_b32_e32 v181, 0xffff0000, v162
	v_lshlrev_b32_e32 v182, 16, v163
	v_and_b32_e32 v183, 0xffff0000, v163
	s_add_i32 s100, s37, 36
	s_cmp_ge_i32 s100, s36
	s_cselect_b32 s101, 1, 0
	s_cmp_lt_i32 s100, s31
	s_cselect_b32 s38, 1, 0
	s_and_b32 s101, s101, s38
	s_cbranch_scc1 .Lcv_ok36
	v_mov_b32_e32 v176, 0
	v_mov_b32_e32 v177, 0
	v_mov_b32_e32 v178, 0
	v_mov_b32_e32 v179, 0
	v_mov_b32_e32 v180, 0
	v_mov_b32_e32 v181, 0
	v_mov_b32_e32 v182, 0
	v_mov_b32_e32 v183, 0
.Lcv_ok36:
	v_pk_fma_f32 v[70:71], v[40:41], v[176:177], v[70:71]
	v_pk_fma_f32 v[66:67], v[42:43], v[178:179], v[66:67]
	v_pk_fma_f32 v[68:69], v[44:45], v[180:181], v[68:69]
	v_pk_fma_f32 v[64:65], v[46:47], v[182:183], v[64:65]
	v_pk_fma_f32 v[62:63], v[32:33], v[176:177], v[62:63]
	v_pk_fma_f32 v[58:59], v[34:35], v[178:179], v[58:59]
	v_pk_fma_f32 v[60:61], v[36:37], v[180:181], v[60:61]
	v_pk_fma_f32 v[56:57], v[38:39], v[182:183], v[56:57]
	s_waitcnt vmcnt(0)
	v_lshlrev_b32_e32 v186, 16, v164
	v_and_b32_e32 v187, 0xffff0000, v164
	v_lshlrev_b32_e32 v190, 16, v165
	v_and_b32_e32 v191, 0xffff0000, v165
	v_lshlrev_b32_e32 v192, 16, v166
	v_and_b32_e32 v193, 0xffff0000, v166
	v_lshlrev_b32_e32 v194, 16, v167
	v_and_b32_e32 v195, 0xffff0000, v167
	s_add_i32 s100, s37, 37
	s_cmp_ge_i32 s100, s36
	s_cselect_b32 s101, 1, 0
	s_cmp_lt_i32 s100, s31
	s_cselect_b32 s38, 1, 0
	s_and_b32 s101, s101, s38
	s_cbranch_scc1 .Lcv_ok37
	v_mov_b32_e32 v186, 0
	v_mov_b32_e32 v187, 0
	v_mov_b32_e32 v190, 0
	v_mov_b32_e32 v191, 0
	v_mov_b32_e32 v192, 0
	v_mov_b32_e32 v193, 0
	v_mov_b32_e32 v194, 0
	v_mov_b32_e32 v195, 0
.Lcv_ok37:
	v_pk_fma_f32 v[62:63], v[40:41], v[186:187], v[62:63]
	v_pk_fma_f32 v[58:59], v[42:43], v[190:191], v[58:59]
	v_pk_fma_f32 v[60:61], v[44:45], v[192:193], v[60:61]
	v_pk_fma_f32 v[56:57], v[46:47], v[194:195], v[56:57]
	s_barrier
	s_branch .LBB0_590
